# UPCONV epilogue body rewritten by hand: conv taps as DPP-fused fmac, packed gelu math, weight loads hoisted
# speedup vs baseline: 1.0080x; 1.0080x over previous
;     __device__ __forceinline__ void operator()(const f32x4 (&acc)[2][2][4][2], const Unit& u, int wr, int wc, int fr, int fq) const {
;     ...
;             for (int ai = 0; ai < 2; ++ai)
; #pragma unroll
;                 for (int m = 0; m < 4; ++m) rs[ai][m] = rsqrtf(ss[row0 + ai * HALF + m * 16] * (1.f / 2048.f) + 1e-6f);
; #pragma unroll
;             for (int ai = 0; ai < 2; ++ai) {
;                 const int slab = u.pm * 4 + ai * 2 + wr;
;                 if (fr < 2) {
; #pragma unroll
;                     for (int bj = 0; bj < 2; ++bj)
; #pragma unroll
;                         for (int n = 0; n < 2; ++n) *(f32x4*)(raw + (size_t)(slab * 4 + fr) * NUPc + tcol + bj * 128 + 4 * n) = acc[ai][bj][0][n] * rs[ai][0];
;                 }
;                 if (fr >= 14) {
; #pragma unroll
;                     for (int bj = 0; bj < 2; ++bj)
; #pragma unroll
;                         for (int n = 0; n < 2; ++n) *(f32x4*)(raw + (size_t)(slab * 4 + fr - 12) * NUPc + tcol + bj * 128 + 4 * n) = acc[ai][bj][3][n] * rs[ai][3];
;                 }
;     ...
;                 const f32x4 wg0 = *(const f32x4*)(bias + c), wg1 = *(const f32x4*)(bias + NUPc + c), wg2 = *(const f32x4*)(bias + 2 * NUPc + c), bg = *(const f32x4*)(xin + c);
;                 const f32x4 wv0 = *(const f32x4*)(bias + DFFc + c), wv1 = *(const f32x4*)(bias + NUPc + DFFc + c), wv2 = *(const f32x4*)(bias + 2 * NUPc + DFFc + c), bv = *(const f32x4*)(xin + DFFc + c);
.LBB0_46:
	v_lshl_or_b32 v201, s65, 7, v216
	v_lshlrev_b32_e32 v205, 2, v201
	global_load_dwordx4 v[218:221], v205, s[18:19]
	global_load_dwordx4 v[222:225], v205, s[20:21]
	global_load_dwordx4 v[226:229], v205, s[26:27]
	global_load_dwordx4 v[230:233], v205, s[28:29]
	global_load_dwordx4 v[234:237], v205, s[30:31]
	global_load_dwordx4 v[238:241], v205, s[38:39]
	global_load_dwordx4 v[242:245], v205, s[34:35]
	global_load_dwordx4 v[246:249], v205, s[36:37]
	v_lshl_add_u32 v186, s66, 8, v213
	v_ashrrev_i32_e32 v187, 31, v186
	v_lshl_add_u64 v[106:107], v[186:187], 2, s[22:23]
	global_load_dword v108, v[106:107], off
	s_mov_b32 s67, 0x800000
	s_lshl_b32 s41, s66, 2
	s_add_i32 s41, s41, s56
	s_waitcnt vmcnt(0)
	v_fmamk_f32 v108, v108, 0x3a000000, v197
	v_cmp_gt_f32_e32 vcc, s67, v108
	v_mul_f32_e32 v109, 0x4b800000, v108
	s_nop 0
	v_cndmask_b32_e32 v108, v108, v109, vcc
	v_rsq_f32_e32 v108, v108
	s_nop 0
	v_mul_f32_e32 v109, 0x45800000, v108
	v_cndmask_b32_e32 v188, v108, v109, vcc
	global_load_dword v187, v[106:107], off offset:64
	global_load_dword v179, v[106:107], off offset:128
	global_load_dword v110, v[106:107], off offset:192
	global_load_dword v109, v[106:107], off offset:512
	global_load_dword v185, v[106:107], off offset:576
	global_load_dword v183, v[106:107], off offset:640
	global_load_dword v108, v[106:107], off offset:704
	v_lshl_or_b32 v106, s65, 8, v216
	v_ashrrev_i32_e32 v107, 31, v106
	s_and_saveexec_b64 s[48:49], s[0:1]
	v_readlane_b32 s68, v254, 10
	v_readlane_b32 s69, v254, 11
	s_cbranch_execz .LBB0_48
	v_lshl_or_b32 v111, s41, 2, v212
	v_mov_b64_e32 v[116:117], s[16:17]
	s_mov_b32 s43, 0xb000
	v_mad_i64_i32 v[116:117], s[50:51], v111, s43, v[116:117]
	v_pk_mul_f32 v[114:115], v[156:157], v[188:189] op_sel_hi:[1,0]
	v_pk_mul_f32 v[112:113], v[154:155], v[188:189] op_sel_hi:[1,0]
	v_lshl_add_u64 v[116:117], v[106:107], 2, v[116:117]
	global_store_dwordx4 v[116:117], v[112:115], off
	s_nop 1
	v_pk_mul_f32 v[114:115], v[64:65], v[188:189] op_sel_hi:[1,0]
	v_pk_mul_f32 v[112:113], v[62:63], v[188:189] op_sel_hi:[1,0]
	global_store_dwordx4 v[116:117], v[112:115], off offset:16
	s_nop 1
	v_pk_mul_f32 v[114:115], v[136:137], v[188:189] op_sel_hi:[1,0]
	v_pk_mul_f32 v[112:113], v[134:135], v[188:189] op_sel_hi:[1,0]
	global_store_dwordx4 v[116:117], v[112:115], off offset:512
	s_nop 1
	v_pk_mul_f32 v[114:115], v[60:61], v[188:189] op_sel_hi:[1,0]
	v_pk_mul_f32 v[112:113], v[58:59], v[188:189] op_sel_hi:[1,0]
	global_store_dwordx4 v[116:117], v[112:115], off offset:528

; __device__ __forceinline__ unsigned cvt_pk_bf16(float lo, float hi) { unsigned r; asm volatile("v_cvt_pk_bf16_f32 %0, %1, %2" : "=v"(r) : "v"(lo), "v"(hi)); return r; }
; __device__ __forceinline__ f32x4 gelu4(f32x4 v) { return (f32x4){gelu_t(v[0]), gelu_t(v[1]), gelu_t(v[2]), gelu_t(v[3])}; }
; template <int CTRL> __device__ __forceinline__ f32x4 dpp4(f32x4 v) { return (f32x4){dpp_f<CTRL>(v[0]), dpp_f<CTRL>(v[1]), dpp_f<CTRL>(v[2]), dpp_f<CTRL>(v[3])}; }
;     __device__ __forceinline__ void operator()(const f32x4 (&acc)[2][2][4][2], const Unit& u, int wr, int wc, int fr, int fq) const {
;     ...
;                 for (int m = 0; m < 4; ++m) rs[ai][m] = rsqrtf(ss[row0 + ai * HALF + m * 16] * (1.f / 2048.f) + 1e-6f);
;     ...
;                 const f32x4 wg0 = *(const f32x4*)(bias + c), wg1 = *(const f32x4*)(bias + NUPc + c), wg2 = *(const f32x4*)(bias + 2 * NUPc + c), bg = *(const f32x4*)(xin + c);
;                 const f32x4 wv0 = *(const f32x4*)(bias + DFFc + c), wv1 = *(const f32x4*)(bias + NUPc + DFFc + c), wv2 = *(const f32x4*)(bias + 2 * NUPc + DFFc + c), bv = *(const f32x4*)(xin + DFFc + c);
; #pragma unroll
;                 for (int ai = 0; ai < 2; ++ai) {
;                     f32x4 pg1 = (f32x4){0.f, 0.f, 0.f, 0.f}, pg2 = pg1, pv1 = pg1, pv2 = pg1;
; #pragma unroll
;                     for (int m = 0; m < 4; ++m) {
;                         const f32x4 g = acc[ai][0][m][n] * rs[ai][m], v = acc[ai][1][m][n] * rs[ai][m];
;                         const f32x4 g1 = dpp4<0x121>(g), g2 = dpp4<0x122>(g), v1 = dpp4<0x121>(v), v2 = dpp4<0x122>(v);
;                         const f32x4 gp1 = (fr >= 1) ? g1 : pg1, gp2 = (fr >= 2) ? g2 : pg2, vp1 = (fr >= 1) ? v1 : pv1, vp2 = (fr >= 2) ? v2 : pv2;
;                         const f32x4 cgt = bg + wg0 * g + wg1 * gp1 + wg2 * gp2, cvl = bv + wv0 * v + wv1 * vp1 + wv2 * vp2;
;                         const f32x4 o = gelu4(cgt) * cvl;
;                         typedef unsigned u32x2e __attribute__((ext_vector_type(2)));
;                         u32x2e w; w.x = cvt_pk_bf16(o[0], o[1]); w.y = cvt_pk_bf16(o[2], o[3]);
;                         if (!(m == 0 && fr < 2)) *(u32x2e*)((bf16_t*)O + (size_t)(row0 + ai * HALF + m * 16) * DFFc + c) = w;
;                         pg1 = g1; pg2 = g2; pv1 = v1; pv2 = v2;
.LBB0_54:
	s_or_b64 exec, exec, s[48:49]
	v_fmamk_f32 v187, v187, 0x3a000000, v197
	v_fmamk_f32 v179, v179, 0x3a000000, v197
	v_fmamk_f32 v185, v185, 0x3a000000, v197
	v_fmamk_f32 v183, v183, 0x3a000000, v197
	v_cmp_gt_f32_e32 vcc, s67, v187
	v_cmp_gt_f32_e64 s[48:49], s67, v179
	v_cmp_gt_f32_e64 s[50:51], s67, v185
	v_cmp_gt_f32_e64 s[52:53], s67, v183
	v_mul_f32_e32 v181, 0x4b800000, v187
	v_mul_f32_e32 v189, 0x4b800000, v179
	v_mul_f32_e32 v191, 0x4b800000, v185
	v_mul_f32_e32 v193, 0x4b800000, v183
	v_cndmask_b32_e32 v187, v187, v181, vcc
	v_cndmask_b32_e64 v179, v179, v189, s[48:49]
	v_cndmask_b32_e64 v185, v185, v191, s[50:51]
	v_cndmask_b32_e64 v183, v183, v193, s[52:53]
	v_rsq_f32_e32 v187, v187
	v_rsq_f32_e32 v179, v179
	v_rsq_f32_e32 v185, v185
	v_rsq_f32_e32 v183, v183
	v_mul_f32_e32 v181, 0x45800000, v187
	v_mul_f32_e32 v189, 0x45800000, v179
	v_mul_f32_e32 v191, 0x45800000, v185
	v_mul_f32_e32 v193, 0x45800000, v183
	v_cndmask_b32_e32 v190, v187, v181, vcc
	v_cndmask_b32_e64 v192, v179, v189, s[48:49]
	v_cndmask_b32_e64 v180, v185, v191, s[50:51]
	v_cndmask_b32_e64 v200, v183, v193, s[52:53]
	v_mov_b32_e32 v132, 0xbdd2d3e8
	v_mov_b32_e32 v250, 1.0
	v_lshlrev_b32_e32 v199, 1, v201
	s_movk_i32 s41, 0x2c00
	v_mad_u32_u24 v199, v186, s41, v199
	v_pk_mul_f32 v[154:155], v[154:155], v[188:189] op_sel_hi:[1,0]
	v_pk_mul_f32 v[156:157], v[156:157], v[188:189] op_sel_hi:[1,0]
	v_pk_mul_f32 v[134:135], v[134:135], v[188:189] op_sel_hi:[1,0]
	v_pk_mul_f32 v[136:137], v[136:137], v[188:189] op_sel_hi:[1,0]
	v_pk_fma_f32 v[106:107], v[154:155], v[218:219], v[222:223]
	v_pk_fma_f32 v[108:109], v[156:157], v[220:221], v[224:225]
	v_pk_fma_f32 v[110:111], v[134:135], v[234:235], v[238:239]
	v_pk_fma_f32 v[112:113], v[136:137], v[236:237], v[240:241]
	v_fmac_f32_dpp v106, v154, v226 row_shr:1 row_mask:0xf bank_mask:0xf
	v_fmac_f32_dpp v107, v155, v227 row_shr:1 row_mask:0xf bank_mask:0xf
	v_fmac_f32_dpp v108, v156, v228 row_shr:1 row_mask:0xf bank_mask:0xf
	v_fmac_f32_dpp v109, v157, v229 row_shr:1 row_mask:0xf bank_mask:0xf
	v_fmac_f32_dpp v110, v134, v242 row_shr:1 row_mask:0xf bank_mask:0xf
	v_fmac_f32_dpp v111, v135, v243 row_shr:1 row_mask:0xf bank_mask:0xf
	v_fmac_f32_dpp v112, v136, v244 row_shr:1 row_mask:0xf bank_mask:0xf
	v_fmac_f32_dpp v113, v137, v245 row_shr:1 row_mask:0xf bank_mask:0xf
	v_fmac_f32_dpp v106, v154, v230 row_shr:2 row_mask:0xf bank_mask:0xf
	v_fmac_f32_dpp v107, v155, v231 row_shr:2 row_mask:0xf bank_mask:0xf
	v_fmac_f32_dpp v108, v156, v232 row_shr:2 row_mask:0xf bank_mask:0xf
	v_fmac_f32_dpp v109, v157, v233 row_shr:2 row_mask:0xf bank_mask:0xf
	v_fmac_f32_dpp v110, v134, v246 row_shr:2 row_mask:0xf bank_mask:0xf
	v_fmac_f32_dpp v111, v135, v247 row_shr:2 row_mask:0xf bank_mask:0xf
	v_fmac_f32_dpp v112, v136, v248 row_shr:2 row_mask:0xf bank_mask:0xf
	v_fmac_f32_dpp v113, v137, v249 row_shr:2 row_mask:0xf bank_mask:0xf
	v_pk_mul_f32 v[114:115], v[106:107], v[106:107]
	v_pk_mul_f32 v[116:117], v[108:109], v[108:109]
	v_pk_fma_f32 v[114:115], v[114:115], v[132:133], v[196:197] op_sel_hi:[1,0,0]
	v_pk_fma_f32 v[116:117], v[116:117], v[132:133], v[196:197] op_sel_hi:[1,0,0]
	v_pk_mul_f32 v[114:115], v[106:107], v[114:115]
	v_pk_mul_f32 v[116:117], v[108:109], v[116:117]
	v_exp_f32_e32 v114, v114
	v_exp_f32_e32 v115, v115
	v_exp_f32_e32 v116, v116
	v_exp_f32_e32 v117, v117
	v_pk_add_f32 v[114:115], v[114:115], v[250:251] op_sel_hi:[1,0]
	v_pk_add_f32 v[116:117], v[116:117], v[250:251] op_sel_hi:[1,0]
	v_rcp_f32_e32 v114, v114
	v_rcp_f32_e32 v115, v115
	v_rcp_f32_e32 v116, v116
	v_rcp_f32_e32 v117, v117
	v_pk_mul_f32 v[114:115], v[106:107], v[114:115]
	v_pk_mul_f32 v[116:117], v[108:109], v[116:117]
	v_pk_mul_f32 v[114:115], v[110:111], v[114:115]
	v_pk_mul_f32 v[116:117], v[112:113], v[116:117]
	v_cvt_pk_bf16_f32 v114, v114, v115
	v_cvt_pk_bf16_f32 v115, v116, v117
	s_and_saveexec_b64 s[48:49], s[10:11]
	global_store_dwordx2 v199, v[114:115], s[68:69]
	s_or_b64 exec, exec, s[48:49]
	v_pk_mul_f32 v[150:151], v[150:151], v[190:191] op_sel_hi:[1,0]
	v_pk_mul_f32 v[152:153], v[152:153], v[190:191] op_sel_hi:[1,0]
	v_pk_mul_f32 v[146:147], v[146:147], v[190:191] op_sel_hi:[1,0]
	v_pk_mul_f32 v[148:149], v[148:149], v[190:191] op_sel_hi:[1,0]
	v_pk_fma_f32 v[118:119], v[150:151], v[218:219], v[222:223]
	v_pk_fma_f32 v[120:121], v[152:153], v[220:221], v[224:225]
	v_pk_fma_f32 v[122:123], v[146:147], v[234:235], v[238:239]
	v_pk_fma_f32 v[124:125], v[148:149], v[236:237], v[240:241]
	v_fmac_f32_dpp v118, v150, v226 row_shr:1 row_mask:0xf bank_mask:0xf
	v_fmac_f32_dpp v119, v151, v227 row_shr:1 row_mask:0xf bank_mask:0xf
	v_fmac_f32_dpp v120, v152, v228 row_shr:1 row_mask:0xf bank_mask:0xf
	v_fmac_f32_dpp v121, v153, v229 row_shr:1 row_mask:0xf bank_mask:0xf
	v_fmac_f32_dpp v122, v146, v242 row_shr:1 row_mask:0xf bank_mask:0xf
	v_fmac_f32_dpp v123, v147, v243 row_shr:1 row_mask:0xf bank_mask:0xf
	v_fmac_f32_dpp v124, v148, v244 row_shr:1 row_mask:0xf bank_mask:0xf
	v_fmac_f32_dpp v125, v149, v245 row_shr:1 row_mask:0xf bank_mask:0xf
	v_fmac_f32_dpp v118, v150, v230 row_shr:2 row_mask:0xf bank_mask:0xf
	v_fmac_f32_dpp v119, v151, v231 row_shr:2 row_mask:0xf bank_mask:0xf
	v_fmac_f32_dpp v120, v152, v232 row_shr:2 row_mask:0xf bank_mask:0xf
	v_fmac_f32_dpp v121, v153, v233 row_shr:2 row_mask:0xf bank_mask:0xf
	v_fmac_f32_dpp v122, v146, v246 row_shr:2 row_mask:0xf bank_mask:0xf
	v_fmac_f32_dpp v123, v147, v247 row_shr:2 row_mask:0xf bank_mask:0xf
	v_fmac_f32_dpp v124, v148, v248 row_shr:2 row_mask:0xf bank_mask:0xf
	v_fmac_f32_dpp v125, v149, v249 row_shr:2 row_mask:0xf bank_mask:0xf
	v_fmac_f32_dpp v118, v154, v226 row_shl:15 row_mask:0xf bank_mask:0xf
; __device__ __forceinline__ unsigned cvt_pk_bf16(float lo, float hi) { unsigned r; asm volatile("v_cvt_pk_bf16_f32 %0, %1, %2" : "=v"(r) : "v"(lo), "v"(hi)); return r; }
; __device__ __forceinline__ f32x4 gelu4(f32x4 v) { return (f32x4){gelu_t(v[0]), gelu_t(v[1]), gelu_t(v[2]), gelu_t(v[3])}; }
; template <int CTRL> __device__ __forceinline__ f32x4 dpp4(f32x4 v) { return (f32x4){dpp_f<CTRL>(v[0]), dpp_f<CTRL>(v[1]), dpp_f<CTRL>(v[2]), dpp_f<CTRL>(v[3])}; }
;     __device__ __forceinline__ void operator()(const f32x4 (&acc)[2][2][4][2], const Unit& u, int wr, int wc, int fr, int fq) const {
;     ...
;                     for (int m = 0; m < 4; ++m) {
;                         const f32x4 g = acc[ai][0][m][n] * rs[ai][m], v = acc[ai][1][m][n] * rs[ai][m];
;                         const f32x4 g1 = dpp4<0x121>(g), g2 = dpp4<0x122>(g), v1 = dpp4<0x121>(v), v2 = dpp4<0x122>(v);
;                         const f32x4 gp1 = (fr >= 1) ? g1 : pg1, gp2 = (fr >= 2) ? g2 : pg2, vp1 = (fr >= 1) ? v1 : pv1, vp2 = (fr >= 2) ? v2 : pv2;
;                         const f32x4 cgt = bg + wg0 * g + wg1 * gp1 + wg2 * gp2, cvl = bv + wv0 * v + wv1 * vp1 + wv2 * vp2;
;                         const f32x4 o = gelu4(cgt) * cvl;
;                         typedef unsigned u32x2e __attribute__((ext_vector_type(2)));
;                         u32x2e w; w.x = cvt_pk_bf16(o[0], o[1]); w.y = cvt_pk_bf16(o[2], o[3]);
;                         if (!(m == 0 && fr < 2)) *(u32x2e*)((bf16_t*)O + (size_t)(row0 + ai * HALF + m * 16) * DFFc + c) = w;
;                         pg1 = g1; pg2 = g2; pv1 = v1; pv2 = v2;
	v_fmac_f32_dpp v119, v155, v227 row_shl:15 row_mask:0xf bank_mask:0xf
	v_fmac_f32_dpp v120, v156, v228 row_shl:15 row_mask:0xf bank_mask:0xf
	v_fmac_f32_dpp v121, v157, v229 row_shl:15 row_mask:0xf bank_mask:0xf
	v_fmac_f32_dpp v122, v134, v242 row_shl:15 row_mask:0xf bank_mask:0xf
	v_fmac_f32_dpp v123, v135, v243 row_shl:15 row_mask:0xf bank_mask:0xf
	v_fmac_f32_dpp v124, v136, v244 row_shl:15 row_mask:0xf bank_mask:0xf
	v_fmac_f32_dpp v125, v137, v245 row_shl:15 row_mask:0xf bank_mask:0xf
	v_fmac_f32_dpp v118, v154, v230 row_shl:14 row_mask:0xf bank_mask:0xf
	v_fmac_f32_dpp v119, v155, v231 row_shl:14 row_mask:0xf bank_mask:0xf
	v_fmac_f32_dpp v120, v156, v232 row_shl:14 row_mask:0xf bank_mask:0xf
	v_fmac_f32_dpp v121, v157, v233 row_shl:14 row_mask:0xf bank_mask:0xf
	v_fmac_f32_dpp v122, v134, v246 row_shl:14 row_mask:0xf bank_mask:0xf
	v_fmac_f32_dpp v123, v135, v247 row_shl:14 row_mask:0xf bank_mask:0xf
	v_fmac_f32_dpp v124, v136, v248 row_shl:14 row_mask:0xf bank_mask:0xf
	v_fmac_f32_dpp v125, v137, v249 row_shl:14 row_mask:0xf bank_mask:0xf
	v_pk_mul_f32 v[126:127], v[118:119], v[118:119]
	v_pk_mul_f32 v[128:129], v[120:121], v[120:121]
	v_pk_fma_f32 v[126:127], v[126:127], v[132:133], v[196:197] op_sel_hi:[1,0,0]
	v_pk_fma_f32 v[128:129], v[128:129], v[132:133], v[196:197] op_sel_hi:[1,0,0]
	v_pk_mul_f32 v[126:127], v[118:119], v[126:127]
	v_pk_mul_f32 v[128:129], v[120:121], v[128:129]
	v_exp_f32_e32 v126, v126
	v_exp_f32_e32 v127, v127
	v_exp_f32_e32 v128, v128
	v_exp_f32_e32 v129, v129
	v_pk_add_f32 v[126:127], v[126:127], v[250:251] op_sel_hi:[1,0]
	v_pk_add_f32 v[128:129], v[128:129], v[250:251] op_sel_hi:[1,0]
	v_rcp_f32_e32 v126, v126
	v_rcp_f32_e32 v127, v127
	v_rcp_f32_e32 v128, v128
	v_rcp_f32_e32 v129, v129
	v_pk_mul_f32 v[126:127], v[118:119], v[126:127]
	v_pk_mul_f32 v[128:129], v[120:121], v[128:129]
	v_pk_mul_f32 v[126:127], v[122:123], v[126:127]
	v_pk_mul_f32 v[128:129], v[124:125], v[128:129]
	v_cvt_pk_bf16_f32 v126, v126, v127
	v_cvt_pk_bf16_f32 v127, v128, v129
	v_add_u32_e32 v131, 0x2c000, v199
	global_store_dwordx2 v131, v[126:127], s[68:69]
	v_pk_mul_f32 v[142:143], v[142:143], v[192:193] op_sel_hi:[1,0]
	v_pk_mul_f32 v[144:145], v[144:145], v[192:193] op_sel_hi:[1,0]
	v_pk_mul_f32 v[138:139], v[138:139], v[192:193] op_sel_hi:[1,0]
	v_pk_mul_f32 v[140:141], v[140:141], v[192:193] op_sel_hi:[1,0]
	v_pk_fma_f32 v[106:107], v[142:143], v[218:219], v[222:223]
	v_pk_fma_f32 v[108:109], v[144:145], v[220:221], v[224:225]
	v_pk_fma_f32 v[110:111], v[138:139], v[234:235], v[238:239]
	v_pk_fma_f32 v[112:113], v[140:141], v[236:237], v[240:241]
	v_fmac_f32_dpp v106, v142, v226 row_shr:1 row_mask:0xf bank_mask:0xf
	v_fmac_f32_dpp v107, v143, v227 row_shr:1 row_mask:0xf bank_mask:0xf
	v_fmac_f32_dpp v108, v144, v228 row_shr:1 row_mask:0xf bank_mask:0xf
	v_fmac_f32_dpp v109, v145, v229 row_shr:1 row_mask:0xf bank_mask:0xf
	v_fmac_f32_dpp v110, v138, v242 row_shr:1 row_mask:0xf bank_mask:0xf
	v_fmac_f32_dpp v111, v139, v243 row_shr:1 row_mask:0xf bank_mask:0xf
	v_fmac_f32_dpp v112, v140, v244 row_shr:1 row_mask:0xf bank_mask:0xf
	v_fmac_f32_dpp v113, v141, v245 row_shr:1 row_mask:0xf bank_mask:0xf
	v_fmac_f32_dpp v106, v142, v230 row_shr:2 row_mask:0xf bank_mask:0xf
	v_fmac_f32_dpp v107, v143, v231 row_shr:2 row_mask:0xf bank_mask:0xf
	v_fmac_f32_dpp v108, v144, v232 row_shr:2 row_mask:0xf bank_mask:0xf
	v_fmac_f32_dpp v109, v145, v233 row_shr:2 row_mask:0xf bank_mask:0xf
	v_fmac_f32_dpp v110, v138, v246 row_shr:2 row_mask:0xf bank_mask:0xf
	v_fmac_f32_dpp v111, v139, v247 row_shr:2 row_mask:0xf bank_mask:0xf
	v_fmac_f32_dpp v112, v140, v248 row_shr:2 row_mask:0xf bank_mask:0xf
	v_fmac_f32_dpp v113, v141, v249 row_shr:2 row_mask:0xf bank_mask:0xf
	v_fmac_f32_dpp v106, v150, v226 row_shl:15 row_mask:0xf bank_mask:0xf
	v_fmac_f32_dpp v107, v151, v227 row_shl:15 row_mask:0xf bank_mask:0xf
	v_fmac_f32_dpp v108, v152, v228 row_shl:15 row_mask:0xf bank_mask:0xf
	v_fmac_f32_dpp v109, v153, v229 row_shl:15 row_mask:0xf bank_mask:0xf
	v_fmac_f32_dpp v110, v146, v242 row_shl:15 row_mask:0xf bank_mask:0xf
	v_fmac_f32_dpp v111, v147, v243 row_shl:15 row_mask:0xf bank_mask:0xf
	v_fmac_f32_dpp v112, v148, v244 row_shl:15 row_mask:0xf bank_mask:0xf
	v_fmac_f32_dpp v113, v149, v245 row_shl:15 row_mask:0xf bank_mask:0xf
	v_fmac_f32_dpp v106, v150, v230 row_shl:14 row_mask:0xf bank_mask:0xf
	v_fmac_f32_dpp v107, v151, v231 row_shl:14 row_mask:0xf bank_mask:0xf
	v_fmac_f32_dpp v108, v152, v232 row_shl:14 row_mask:0xf bank_mask:0xf
	v_fmac_f32_dpp v109, v153, v233 row_shl:14 row_mask:0xf bank_mask:0xf
	v_fmac_f32_dpp v110, v146, v246 row_shl:14 row_mask:0xf bank_mask:0xf
	v_fmac_f32_dpp v111, v147, v247 row_shl:14 row_mask:0xf bank_mask:0xf
	v_fmac_f32_dpp v112, v148, v248 row_shl:14 row_mask:0xf bank_mask:0xf
	v_fmac_f32_dpp v113, v149, v249 row_shl:14 row_mask:0xf bank_mask:0xf
	v_pk_mul_f32 v[114:115], v[106:107], v[106:107]
	v_pk_mul_f32 v[116:117], v[108:109], v[108:109]
	v_pk_fma_f32 v[114:115], v[114:115], v[132:133], v[196:197] op_sel_hi:[1,0,0]
	v_pk_fma_f32 v[116:117], v[116:117], v[132:133], v[196:197] op_sel_hi:[1,0,0]
	v_pk_mul_f32 v[114:115], v[106:107], v[114:115]
	v_pk_mul_f32 v[116:117], v[108:109], v[116:117]
	v_exp_f32_e32 v114, v114
	v_exp_f32_e32 v115, v115
	v_exp_f32_e32 v116, v116
	v_exp_f32_e32 v117, v117
	v_pk_add_f32 v[114:115], v[114:115], v[250:251] op_sel_hi:[1,0]
	v_pk_add_f32 v[116:117], v[116:117], v[250:251] op_sel_hi:[1,0]
	v_rcp_f32_e32 v114, v114
	v_rcp_f32_e32 v115, v115
	v_rcp_f32_e32 v116, v116
	v_rcp_f32_e32 v117, v117
	v_pk_mul_f32 v[114:115], v[106:107], v[114:115]
	v_pk_mul_f32 v[116:117], v[108:109], v[116:117]
; __device__ __forceinline__ unsigned cvt_pk_bf16(float lo, float hi) { unsigned r; asm volatile("v_cvt_pk_bf16_f32 %0, %1, %2" : "=v"(r) : "v"(lo), "v"(hi)); return r; }
; __device__ __forceinline__ f32x4 gelu4(f32x4 v) { return (f32x4){gelu_t(v[0]), gelu_t(v[1]), gelu_t(v[2]), gelu_t(v[3])}; }
; template <int CTRL> __device__ __forceinline__ f32x4 dpp4(f32x4 v) { return (f32x4){dpp_f<CTRL>(v[0]), dpp_f<CTRL>(v[1]), dpp_f<CTRL>(v[2]), dpp_f<CTRL>(v[3])}; }
;     __device__ __forceinline__ void operator()(const f32x4 (&acc)[2][2][4][2], const Unit& u, int wr, int wc, int fr, int fq) const {
;     ...
;                 const f32x4 wg0 = *(const f32x4*)(bias + c), wg1 = *(const f32x4*)(bias + NUPc + c), wg2 = *(const f32x4*)(bias + 2 * NUPc + c), bg = *(const f32x4*)(xin + c);
;                 const f32x4 wv0 = *(const f32x4*)(bias + DFFc + c), wv1 = *(const f32x4*)(bias + NUPc + DFFc + c), wv2 = *(const f32x4*)(bias + 2 * NUPc + DFFc + c), bv = *(const f32x4*)(xin + DFFc + c);
;     ...
;                     for (int m = 0; m < 4; ++m) {
;                         const f32x4 g = acc[ai][0][m][n] * rs[ai][m], v = acc[ai][1][m][n] * rs[ai][m];
;                         const f32x4 g1 = dpp4<0x121>(g), g2 = dpp4<0x122>(g), v1 = dpp4<0x121>(v), v2 = dpp4<0x122>(v);
;                         const f32x4 gp1 = (fr >= 1) ? g1 : pg1, gp2 = (fr >= 2) ? g2 : pg2, vp1 = (fr >= 1) ? v1 : pv1, vp2 = (fr >= 2) ? v2 : pv2;
;                         const f32x4 cgt = bg + wg0 * g + wg1 * gp1 + wg2 * gp2, cvl = bv + wv0 * v + wv1 * vp1 + wv2 * vp2;
;                         const f32x4 o = gelu4(cgt) * cvl;
;                         typedef unsigned u32x2e __attribute__((ext_vector_type(2)));
;                         u32x2e w; w.x = cvt_pk_bf16(o[0], o[1]); w.y = cvt_pk_bf16(o[2], o[3]);
;                         if (!(m == 0 && fr < 2)) *(u32x2e*)((bf16_t*)O + (size_t)(row0 + ai * HALF + m * 16) * DFFc + c) = w;
;                         pg1 = g1; pg2 = g2; pv1 = v1; pv2 = v2;
	v_pk_mul_f32 v[114:115], v[110:111], v[114:115]
	v_pk_mul_f32 v[116:117], v[112:113], v[116:117]
	v_cvt_pk_bf16_f32 v114, v114, v115
	v_cvt_pk_bf16_f32 v115, v116, v117
	v_add_u32_e32 v130, 0x58000, v199
	global_store_dwordx2 v130, v[114:115], s[68:69]
	v_pk_mul_f32 v[102:103], v[102:103], v[184:185] op_sel_hi:[1,0]
	v_pk_mul_f32 v[104:105], v[104:105], v[184:185] op_sel_hi:[1,0]
	v_pk_mul_f32 v[98:99], v[98:99], v[184:185] op_sel_hi:[1,0]
	v_pk_mul_f32 v[100:101], v[100:101], v[184:185] op_sel_hi:[1,0]
	v_pk_fma_f32 v[118:119], v[102:103], v[218:219], v[222:223]
	v_pk_fma_f32 v[120:121], v[104:105], v[220:221], v[224:225]
	v_pk_fma_f32 v[122:123], v[98:99], v[234:235], v[238:239]
	v_pk_fma_f32 v[124:125], v[100:101], v[236:237], v[240:241]
	v_fmac_f32_dpp v118, v102, v226 row_shr:1 row_mask:0xf bank_mask:0xf
	v_fmac_f32_dpp v119, v103, v227 row_shr:1 row_mask:0xf bank_mask:0xf
	v_fmac_f32_dpp v120, v104, v228 row_shr:1 row_mask:0xf bank_mask:0xf
	v_fmac_f32_dpp v121, v105, v229 row_shr:1 row_mask:0xf bank_mask:0xf
	v_fmac_f32_dpp v122, v98, v242 row_shr:1 row_mask:0xf bank_mask:0xf
	v_fmac_f32_dpp v123, v99, v243 row_shr:1 row_mask:0xf bank_mask:0xf
	v_fmac_f32_dpp v124, v100, v244 row_shr:1 row_mask:0xf bank_mask:0xf
	v_fmac_f32_dpp v125, v101, v245 row_shr:1 row_mask:0xf bank_mask:0xf
	v_fmac_f32_dpp v118, v102, v230 row_shr:2 row_mask:0xf bank_mask:0xf
	v_fmac_f32_dpp v119, v103, v231 row_shr:2 row_mask:0xf bank_mask:0xf
	v_fmac_f32_dpp v120, v104, v232 row_shr:2 row_mask:0xf bank_mask:0xf
	v_fmac_f32_dpp v121, v105, v233 row_shr:2 row_mask:0xf bank_mask:0xf
	v_fmac_f32_dpp v122, v98, v246 row_shr:2 row_mask:0xf bank_mask:0xf
	v_fmac_f32_dpp v123, v99, v247 row_shr:2 row_mask:0xf bank_mask:0xf
	v_fmac_f32_dpp v124, v100, v248 row_shr:2 row_mask:0xf bank_mask:0xf
	v_fmac_f32_dpp v125, v101, v249 row_shr:2 row_mask:0xf bank_mask:0xf
	v_fmac_f32_dpp v118, v142, v226 row_shl:15 row_mask:0xf bank_mask:0xf
	v_fmac_f32_dpp v119, v143, v227 row_shl:15 row_mask:0xf bank_mask:0xf
	v_fmac_f32_dpp v120, v144, v228 row_shl:15 row_mask:0xf bank_mask:0xf
	v_fmac_f32_dpp v121, v145, v229 row_shl:15 row_mask:0xf bank_mask:0xf
	v_fmac_f32_dpp v122, v138, v242 row_shl:15 row_mask:0xf bank_mask:0xf
	v_fmac_f32_dpp v123, v139, v243 row_shl:15 row_mask:0xf bank_mask:0xf
	v_fmac_f32_dpp v124, v140, v244 row_shl:15 row_mask:0xf bank_mask:0xf
	v_fmac_f32_dpp v125, v141, v245 row_shl:15 row_mask:0xf bank_mask:0xf
	v_fmac_f32_dpp v118, v142, v230 row_shl:14 row_mask:0xf bank_mask:0xf
	v_fmac_f32_dpp v119, v143, v231 row_shl:14 row_mask:0xf bank_mask:0xf
	v_fmac_f32_dpp v120, v144, v232 row_shl:14 row_mask:0xf bank_mask:0xf
	v_fmac_f32_dpp v121, v145, v233 row_shl:14 row_mask:0xf bank_mask:0xf
	v_fmac_f32_dpp v122, v138, v246 row_shl:14 row_mask:0xf bank_mask:0xf
	v_fmac_f32_dpp v123, v139, v247 row_shl:14 row_mask:0xf bank_mask:0xf
	v_fmac_f32_dpp v124, v140, v248 row_shl:14 row_mask:0xf bank_mask:0xf
	v_fmac_f32_dpp v125, v141, v249 row_shl:14 row_mask:0xf bank_mask:0xf
	v_pk_mul_f32 v[126:127], v[118:119], v[118:119]
	v_pk_mul_f32 v[128:129], v[120:121], v[120:121]
	v_pk_fma_f32 v[126:127], v[126:127], v[132:133], v[196:197] op_sel_hi:[1,0,0]
	v_pk_fma_f32 v[128:129], v[128:129], v[132:133], v[196:197] op_sel_hi:[1,0,0]
	v_pk_mul_f32 v[126:127], v[118:119], v[126:127]
	v_pk_mul_f32 v[128:129], v[120:121], v[128:129]
	v_exp_f32_e32 v126, v126
	v_exp_f32_e32 v127, v127
	v_exp_f32_e32 v128, v128
	v_exp_f32_e32 v129, v129
	v_pk_add_f32 v[126:127], v[126:127], v[250:251] op_sel_hi:[1,0]
	v_pk_add_f32 v[128:129], v[128:129], v[250:251] op_sel_hi:[1,0]
	v_rcp_f32_e32 v126, v126
	v_rcp_f32_e32 v127, v127
	v_rcp_f32_e32 v128, v128
	v_rcp_f32_e32 v129, v129
	v_pk_mul_f32 v[126:127], v[118:119], v[126:127]
	v_pk_mul_f32 v[128:129], v[120:121], v[128:129]
	v_pk_mul_f32 v[126:127], v[122:123], v[126:127]
	v_pk_mul_f32 v[128:129], v[124:125], v[128:129]
	v_cvt_pk_bf16_f32 v126, v126, v127
	v_cvt_pk_bf16_f32 v127, v128, v129
	v_add_u32_e32 v131, 0x84000, v199
	global_store_dwordx2 v131, v[126:127], s[68:69]
	global_load_dwordx4 v[154:157], v205, s[18:19] offset:16
	global_load_dwordx4 v[150:153], v205, s[20:21] offset:16
	global_load_dwordx4 v[142:145], v205, s[26:27] offset:16
	global_load_dwordx4 v[102:105], v205, s[28:29] offset:16
	global_load_dwordx4 v[134:137], v205, s[30:31] offset:16
	global_load_dwordx4 v[146:149], v205, s[38:39] offset:16
	global_load_dwordx4 v[138:141], v205, s[34:35] offset:16
	global_load_dwordx4 v[98:101], v205, s[36:37] offset:16
	v_pk_mul_f32 v[94:95], v[94:95], v[182:183] op_sel_hi:[1,0]
	v_pk_mul_f32 v[96:97], v[96:97], v[182:183] op_sel_hi:[1,0]
	v_pk_mul_f32 v[90:91], v[90:91], v[182:183] op_sel_hi:[1,0]
	v_pk_mul_f32 v[92:93], v[92:93], v[182:183] op_sel_hi:[1,0]
	v_pk_fma_f32 v[106:107], v[94:95], v[218:219], v[222:223]
	v_pk_fma_f32 v[108:109], v[96:97], v[220:221], v[224:225]
	v_pk_fma_f32 v[110:111], v[90:91], v[234:235], v[238:239]
	v_pk_fma_f32 v[112:113], v[92:93], v[236:237], v[240:241]
	v_fmac_f32_dpp v106, v94, v226 row_shr:1 row_mask:0xf bank_mask:0xf
	v_fmac_f32_dpp v107, v95, v227 row_shr:1 row_mask:0xf bank_mask:0xf
	v_fmac_f32_dpp v108, v96, v228 row_shr:1 row_mask:0xf bank_mask:0xf
	v_fmac_f32_dpp v109, v97, v229 row_shr:1 row_mask:0xf bank_mask:0xf
	v_fmac_f32_dpp v110, v90, v242 row_shr:1 row_mask:0xf bank_mask:0xf
	v_fmac_f32_dpp v111, v91, v243 row_shr:1 row_mask:0xf bank_mask:0xf
	v_fmac_f32_dpp v112, v92, v244 row_shr:1 row_mask:0xf bank_mask:0xf
	v_fmac_f32_dpp v113, v93, v245 row_shr:1 row_mask:0xf bank_mask:0xf
	v_fmac_f32_dpp v106, v94, v230 row_shr:2 row_mask:0xf bank_mask:0xf
; __device__ __forceinline__ unsigned cvt_pk_bf16(float lo, float hi) { unsigned r; asm volatile("v_cvt_pk_bf16_f32 %0, %1, %2" : "=v"(r) : "v"(lo), "v"(hi)); return r; }
; __device__ __forceinline__ f32x4 gelu4(f32x4 v) { return (f32x4){gelu_t(v[0]), gelu_t(v[1]), gelu_t(v[2]), gelu_t(v[3])}; }
; template <int CTRL> __device__ __forceinline__ f32x4 dpp4(f32x4 v) { return (f32x4){dpp_f<CTRL>(v[0]), dpp_f<CTRL>(v[1]), dpp_f<CTRL>(v[2]), dpp_f<CTRL>(v[3])}; }
;     __device__ __forceinline__ void operator()(const f32x4 (&acc)[2][2][4][2], const Unit& u, int wr, int wc, int fr, int fq) const {
;     ...
;                     for (int m = 0; m < 4; ++m) {
;                         const f32x4 g = acc[ai][0][m][n] * rs[ai][m], v = acc[ai][1][m][n] * rs[ai][m];
;                         const f32x4 g1 = dpp4<0x121>(g), g2 = dpp4<0x122>(g), v1 = dpp4<0x121>(v), v2 = dpp4<0x122>(v);
;                         const f32x4 gp1 = (fr >= 1) ? g1 : pg1, gp2 = (fr >= 2) ? g2 : pg2, vp1 = (fr >= 1) ? v1 : pv1, vp2 = (fr >= 2) ? v2 : pv2;
;                         const f32x4 cgt = bg + wg0 * g + wg1 * gp1 + wg2 * gp2, cvl = bv + wv0 * v + wv1 * vp1 + wv2 * vp2;
;                         const f32x4 o = gelu4(cgt) * cvl;
;                         typedef unsigned u32x2e __attribute__((ext_vector_type(2)));
;                         u32x2e w; w.x = cvt_pk_bf16(o[0], o[1]); w.y = cvt_pk_bf16(o[2], o[3]);
;                         if (!(m == 0 && fr < 2)) *(u32x2e*)((bf16_t*)O + (size_t)(row0 + ai * HALF + m * 16) * DFFc + c) = w;
;                         pg1 = g1; pg2 = g2; pv1 = v1; pv2 = v2;
	v_fmac_f32_dpp v107, v95, v231 row_shr:2 row_mask:0xf bank_mask:0xf
	v_fmac_f32_dpp v108, v96, v232 row_shr:2 row_mask:0xf bank_mask:0xf
	v_fmac_f32_dpp v109, v97, v233 row_shr:2 row_mask:0xf bank_mask:0xf
	v_fmac_f32_dpp v110, v90, v246 row_shr:2 row_mask:0xf bank_mask:0xf
	v_fmac_f32_dpp v111, v91, v247 row_shr:2 row_mask:0xf bank_mask:0xf
	v_fmac_f32_dpp v112, v92, v248 row_shr:2 row_mask:0xf bank_mask:0xf
	v_fmac_f32_dpp v113, v93, v249 row_shr:2 row_mask:0xf bank_mask:0xf
	v_pk_mul_f32 v[114:115], v[106:107], v[106:107]
	v_pk_mul_f32 v[116:117], v[108:109], v[108:109]
	v_pk_fma_f32 v[114:115], v[114:115], v[132:133], v[196:197] op_sel_hi:[1,0,0]
	v_pk_fma_f32 v[116:117], v[116:117], v[132:133], v[196:197] op_sel_hi:[1,0,0]
	v_pk_mul_f32 v[114:115], v[106:107], v[114:115]
	v_pk_mul_f32 v[116:117], v[108:109], v[116:117]
	v_exp_f32_e32 v114, v114
	v_exp_f32_e32 v115, v115
	v_exp_f32_e32 v116, v116
	v_exp_f32_e32 v117, v117
	v_pk_add_f32 v[114:115], v[114:115], v[250:251] op_sel_hi:[1,0]
	v_pk_add_f32 v[116:117], v[116:117], v[250:251] op_sel_hi:[1,0]
	v_rcp_f32_e32 v114, v114
	v_rcp_f32_e32 v115, v115
	v_rcp_f32_e32 v116, v116
	v_rcp_f32_e32 v117, v117
	v_pk_mul_f32 v[114:115], v[106:107], v[114:115]
	v_pk_mul_f32 v[116:117], v[108:109], v[116:117]
	v_pk_mul_f32 v[114:115], v[110:111], v[114:115]
	v_pk_mul_f32 v[116:117], v[112:113], v[116:117]
	v_cvt_pk_bf16_f32 v114, v114, v115
	v_cvt_pk_bf16_f32 v115, v116, v117
	v_add_u32_e32 v130, 0x160000, v199
	s_and_saveexec_b64 s[48:49], s[10:11]
	global_store_dwordx2 v130, v[114:115], s[68:69]
	s_or_b64 exec, exec, s[48:49]
	v_pk_mul_f32 v[86:87], v[86:87], v[180:181] op_sel_hi:[1,0]
	v_pk_mul_f32 v[88:89], v[88:89], v[180:181] op_sel_hi:[1,0]
	v_pk_mul_f32 v[82:83], v[82:83], v[180:181] op_sel_hi:[1,0]
	v_pk_mul_f32 v[84:85], v[84:85], v[180:181] op_sel_hi:[1,0]
	v_pk_fma_f32 v[118:119], v[86:87], v[218:219], v[222:223]
	v_pk_fma_f32 v[120:121], v[88:89], v[220:221], v[224:225]
	v_pk_fma_f32 v[122:123], v[82:83], v[234:235], v[238:239]
	v_pk_fma_f32 v[124:125], v[84:85], v[236:237], v[240:241]
	v_fmac_f32_dpp v118, v86, v226 row_shr:1 row_mask:0xf bank_mask:0xf
	v_fmac_f32_dpp v119, v87, v227 row_shr:1 row_mask:0xf bank_mask:0xf
	v_fmac_f32_dpp v120, v88, v228 row_shr:1 row_mask:0xf bank_mask:0xf
	v_fmac_f32_dpp v121, v89, v229 row_shr:1 row_mask:0xf bank_mask:0xf
	v_fmac_f32_dpp v122, v82, v242 row_shr:1 row_mask:0xf bank_mask:0xf
	v_fmac_f32_dpp v123, v83, v243 row_shr:1 row_mask:0xf bank_mask:0xf
	v_fmac_f32_dpp v124, v84, v244 row_shr:1 row_mask:0xf bank_mask:0xf
	v_fmac_f32_dpp v125, v85, v245 row_shr:1 row_mask:0xf bank_mask:0xf
	v_fmac_f32_dpp v118, v86, v230 row_shr:2 row_mask:0xf bank_mask:0xf
	v_fmac_f32_dpp v119, v87, v231 row_shr:2 row_mask:0xf bank_mask:0xf
	v_fmac_f32_dpp v120, v88, v232 row_shr:2 row_mask:0xf bank_mask:0xf
	v_fmac_f32_dpp v121, v89, v233 row_shr:2 row_mask:0xf bank_mask:0xf
	v_fmac_f32_dpp v122, v82, v246 row_shr:2 row_mask:0xf bank_mask:0xf
	v_fmac_f32_dpp v123, v83, v247 row_shr:2 row_mask:0xf bank_mask:0xf
	v_fmac_f32_dpp v124, v84, v248 row_shr:2 row_mask:0xf bank_mask:0xf
	v_fmac_f32_dpp v125, v85, v249 row_shr:2 row_mask:0xf bank_mask:0xf
	v_fmac_f32_dpp v118, v94, v226 row_shl:15 row_mask:0xf bank_mask:0xf
	v_fmac_f32_dpp v119, v95, v227 row_shl:15 row_mask:0xf bank_mask:0xf
	v_fmac_f32_dpp v120, v96, v228 row_shl:15 row_mask:0xf bank_mask:0xf
	v_fmac_f32_dpp v121, v97, v229 row_shl:15 row_mask:0xf bank_mask:0xf
	v_fmac_f32_dpp v122, v90, v242 row_shl:15 row_mask:0xf bank_mask:0xf
	v_fmac_f32_dpp v123, v91, v243 row_shl:15 row_mask:0xf bank_mask:0xf
	v_fmac_f32_dpp v124, v92, v244 row_shl:15 row_mask:0xf bank_mask:0xf
	v_fmac_f32_dpp v125, v93, v245 row_shl:15 row_mask:0xf bank_mask:0xf
	v_fmac_f32_dpp v118, v94, v230 row_shl:14 row_mask:0xf bank_mask:0xf
	v_fmac_f32_dpp v119, v95, v231 row_shl:14 row_mask:0xf bank_mask:0xf
	v_fmac_f32_dpp v120, v96, v232 row_shl:14 row_mask:0xf bank_mask:0xf
	v_fmac_f32_dpp v121, v97, v233 row_shl:14 row_mask:0xf bank_mask:0xf
	v_fmac_f32_dpp v122, v90, v246 row_shl:14 row_mask:0xf bank_mask:0xf
	v_fmac_f32_dpp v123, v91, v247 row_shl:14 row_mask:0xf bank_mask:0xf
	v_fmac_f32_dpp v124, v92, v248 row_shl:14 row_mask:0xf bank_mask:0xf
	v_fmac_f32_dpp v125, v93, v249 row_shl:14 row_mask:0xf bank_mask:0xf
	v_pk_mul_f32 v[126:127], v[118:119], v[118:119]
	v_pk_mul_f32 v[128:129], v[120:121], v[120:121]
	v_pk_fma_f32 v[126:127], v[126:127], v[132:133], v[196:197] op_sel_hi:[1,0,0]
	v_pk_fma_f32 v[128:129], v[128:129], v[132:133], v[196:197] op_sel_hi:[1,0,0]
	v_pk_mul_f32 v[126:127], v[118:119], v[126:127]
	v_pk_mul_f32 v[128:129], v[120:121], v[128:129]
	v_exp_f32_e32 v126, v126
	v_exp_f32_e32 v127, v127
	v_exp_f32_e32 v128, v128
	v_exp_f32_e32 v129, v129
	v_pk_add_f32 v[126:127], v[126:127], v[250:251] op_sel_hi:[1,0]
	v_pk_add_f32 v[128:129], v[128:129], v[250:251] op_sel_hi:[1,0]
	v_rcp_f32_e32 v126, v126
	v_rcp_f32_e32 v127, v127
	v_rcp_f32_e32 v128, v128
	v_rcp_f32_e32 v129, v129
	v_pk_mul_f32 v[126:127], v[118:119], v[126:127]
	v_pk_mul_f32 v[128:129], v[120:121], v[128:129]
	v_pk_mul_f32 v[126:127], v[122:123], v[126:127]
	v_pk_mul_f32 v[128:129], v[124:125], v[128:129]
	v_cvt_pk_bf16_f32 v126, v126, v127
	v_cvt_pk_bf16_f32 v127, v128, v129
	v_add_u32_e32 v131, 0x18c000, v199
	global_store_dwordx2 v131, v[126:127], s[68:69]
	v_pk_mul_f32 v[78:79], v[78:79], v[200:201] op_sel_hi:[1,0]
	v_pk_mul_f32 v[80:81], v[80:81], v[200:201] op_sel_hi:[1,0]
	v_pk_mul_f32 v[74:75], v[74:75], v[200:201] op_sel_hi:[1,0]
	v_pk_mul_f32 v[76:77], v[76:77], v[200:201] op_sel_hi:[1,0]
	v_pk_fma_f32 v[106:107], v[78:79], v[218:219], v[222:223]
; __device__ __forceinline__ unsigned cvt_pk_bf16(float lo, float hi) { unsigned r; asm volatile("v_cvt_pk_bf16_f32 %0, %1, %2" : "=v"(r) : "v"(lo), "v"(hi)); return r; }
; __device__ __forceinline__ f32x4 gelu4(f32x4 v) { return (f32x4){gelu_t(v[0]), gelu_t(v[1]), gelu_t(v[2]), gelu_t(v[3])}; }
; template <int CTRL> __device__ __forceinline__ f32x4 dpp4(f32x4 v) { return (f32x4){dpp_f<CTRL>(v[0]), dpp_f<CTRL>(v[1]), dpp_f<CTRL>(v[2]), dpp_f<CTRL>(v[3])}; }
;     __device__ __forceinline__ void operator()(const f32x4 (&acc)[2][2][4][2], const Unit& u, int wr, int wc, int fr, int fq) const {
;     ...
;                     for (int m = 0; m < 4; ++m) {
;                         const f32x4 g = acc[ai][0][m][n] * rs[ai][m], v = acc[ai][1][m][n] * rs[ai][m];
;                         const f32x4 g1 = dpp4<0x121>(g), g2 = dpp4<0x122>(g), v1 = dpp4<0x121>(v), v2 = dpp4<0x122>(v);
;                         const f32x4 gp1 = (fr >= 1) ? g1 : pg1, gp2 = (fr >= 2) ? g2 : pg2, vp1 = (fr >= 1) ? v1 : pv1, vp2 = (fr >= 2) ? v2 : pv2;
;                         const f32x4 cgt = bg + wg0 * g + wg1 * gp1 + wg2 * gp2, cvl = bv + wv0 * v + wv1 * vp1 + wv2 * vp2;
;                         const f32x4 o = gelu4(cgt) * cvl;
;                         typedef unsigned u32x2e __attribute__((ext_vector_type(2)));
;                         u32x2e w; w.x = cvt_pk_bf16(o[0], o[1]); w.y = cvt_pk_bf16(o[2], o[3]);
;                         if (!(m == 0 && fr < 2)) *(u32x2e*)((bf16_t*)O + (size_t)(row0 + ai * HALF + m * 16) * DFFc + c) = w;
;                         pg1 = g1; pg2 = g2; pv1 = v1; pv2 = v2;
	v_pk_fma_f32 v[108:109], v[80:81], v[220:221], v[224:225]
	v_pk_fma_f32 v[110:111], v[74:75], v[234:235], v[238:239]
	v_pk_fma_f32 v[112:113], v[76:77], v[236:237], v[240:241]
	v_fmac_f32_dpp v106, v78, v226 row_shr:1 row_mask:0xf bank_mask:0xf
	v_fmac_f32_dpp v107, v79, v227 row_shr:1 row_mask:0xf bank_mask:0xf
	v_fmac_f32_dpp v108, v80, v228 row_shr:1 row_mask:0xf bank_mask:0xf
	v_fmac_f32_dpp v109, v81, v229 row_shr:1 row_mask:0xf bank_mask:0xf
	v_fmac_f32_dpp v110, v74, v242 row_shr:1 row_mask:0xf bank_mask:0xf
	v_fmac_f32_dpp v111, v75, v243 row_shr:1 row_mask:0xf bank_mask:0xf
	v_fmac_f32_dpp v112, v76, v244 row_shr:1 row_mask:0xf bank_mask:0xf
	v_fmac_f32_dpp v113, v77, v245 row_shr:1 row_mask:0xf bank_mask:0xf
	v_fmac_f32_dpp v106, v78, v230 row_shr:2 row_mask:0xf bank_mask:0xf
	v_fmac_f32_dpp v107, v79, v231 row_shr:2 row_mask:0xf bank_mask:0xf
	v_fmac_f32_dpp v108, v80, v232 row_shr:2 row_mask:0xf bank_mask:0xf
	v_fmac_f32_dpp v109, v81, v233 row_shr:2 row_mask:0xf bank_mask:0xf
	v_fmac_f32_dpp v110, v74, v246 row_shr:2 row_mask:0xf bank_mask:0xf
	v_fmac_f32_dpp v111, v75, v247 row_shr:2 row_mask:0xf bank_mask:0xf
	v_fmac_f32_dpp v112, v76, v248 row_shr:2 row_mask:0xf bank_mask:0xf
	v_fmac_f32_dpp v113, v77, v249 row_shr:2 row_mask:0xf bank_mask:0xf
	v_fmac_f32_dpp v106, v86, v226 row_shl:15 row_mask:0xf bank_mask:0xf
	v_fmac_f32_dpp v107, v87, v227 row_shl:15 row_mask:0xf bank_mask:0xf
	v_fmac_f32_dpp v108, v88, v228 row_shl:15 row_mask:0xf bank_mask:0xf
	v_fmac_f32_dpp v109, v89, v229 row_shl:15 row_mask:0xf bank_mask:0xf
	v_fmac_f32_dpp v110, v82, v242 row_shl:15 row_mask:0xf bank_mask:0xf
	v_fmac_f32_dpp v111, v83, v243 row_shl:15 row_mask:0xf bank_mask:0xf
	v_fmac_f32_dpp v112, v84, v244 row_shl:15 row_mask:0xf bank_mask:0xf
	v_fmac_f32_dpp v113, v85, v245 row_shl:15 row_mask:0xf bank_mask:0xf
	v_fmac_f32_dpp v106, v86, v230 row_shl:14 row_mask:0xf bank_mask:0xf
	v_fmac_f32_dpp v107, v87, v231 row_shl:14 row_mask:0xf bank_mask:0xf
	v_fmac_f32_dpp v108, v88, v232 row_shl:14 row_mask:0xf bank_mask:0xf
	v_fmac_f32_dpp v109, v89, v233 row_shl:14 row_mask:0xf bank_mask:0xf
	v_fmac_f32_dpp v110, v82, v246 row_shl:14 row_mask:0xf bank_mask:0xf
	v_fmac_f32_dpp v111, v83, v247 row_shl:14 row_mask:0xf bank_mask:0xf
	v_fmac_f32_dpp v112, v84, v248 row_shl:14 row_mask:0xf bank_mask:0xf
	v_fmac_f32_dpp v113, v85, v249 row_shl:14 row_mask:0xf bank_mask:0xf
	v_pk_mul_f32 v[114:115], v[106:107], v[106:107]
	v_pk_mul_f32 v[116:117], v[108:109], v[108:109]
	v_pk_fma_f32 v[114:115], v[114:115], v[132:133], v[196:197] op_sel_hi:[1,0,0]
	v_pk_fma_f32 v[116:117], v[116:117], v[132:133], v[196:197] op_sel_hi:[1,0,0]
	v_pk_mul_f32 v[114:115], v[106:107], v[114:115]
	v_pk_mul_f32 v[116:117], v[108:109], v[116:117]
	v_exp_f32_e32 v114, v114
	v_exp_f32_e32 v115, v115
	v_exp_f32_e32 v116, v116
	v_exp_f32_e32 v117, v117
	v_pk_add_f32 v[114:115], v[114:115], v[250:251] op_sel_hi:[1,0]
	v_pk_add_f32 v[116:117], v[116:117], v[250:251] op_sel_hi:[1,0]
	v_rcp_f32_e32 v114, v114
	v_rcp_f32_e32 v115, v115
	v_rcp_f32_e32 v116, v116
	v_rcp_f32_e32 v117, v117
	v_pk_mul_f32 v[114:115], v[106:107], v[114:115]
	v_pk_mul_f32 v[116:117], v[108:109], v[116:117]
	v_pk_mul_f32 v[114:115], v[110:111], v[114:115]
	v_pk_mul_f32 v[116:117], v[112:113], v[116:117]
	v_cvt_pk_bf16_f32 v114, v114, v115
	v_cvt_pk_bf16_f32 v115, v116, v117
	v_add_u32_e32 v130, 0x1b8000, v199
	global_store_dwordx2 v130, v[114:115], s[68:69]
	v_pk_mul_f32 v[70:71], v[70:71], v[178:179] op_sel_hi:[1,0]
	v_pk_mul_f32 v[72:73], v[72:73], v[178:179] op_sel_hi:[1,0]
	v_pk_mul_f32 v[66:67], v[66:67], v[178:179] op_sel_hi:[1,0]
	v_pk_mul_f32 v[68:69], v[68:69], v[178:179] op_sel_hi:[1,0]
	v_pk_fma_f32 v[118:119], v[70:71], v[218:219], v[222:223]
	v_pk_fma_f32 v[120:121], v[72:73], v[220:221], v[224:225]
	v_pk_fma_f32 v[122:123], v[66:67], v[234:235], v[238:239]
	v_pk_fma_f32 v[124:125], v[68:69], v[236:237], v[240:241]
	v_fmac_f32_dpp v118, v70, v226 row_shr:1 row_mask:0xf bank_mask:0xf
	v_fmac_f32_dpp v119, v71, v227 row_shr:1 row_mask:0xf bank_mask:0xf
	v_fmac_f32_dpp v120, v72, v228 row_shr:1 row_mask:0xf bank_mask:0xf
	v_fmac_f32_dpp v121, v73, v229 row_shr:1 row_mask:0xf bank_mask:0xf
	v_fmac_f32_dpp v122, v66, v242 row_shr:1 row_mask:0xf bank_mask:0xf
	v_fmac_f32_dpp v123, v67, v243 row_shr:1 row_mask:0xf bank_mask:0xf
	v_fmac_f32_dpp v124, v68, v244 row_shr:1 row_mask:0xf bank_mask:0xf
	v_fmac_f32_dpp v125, v69, v245 row_shr:1 row_mask:0xf bank_mask:0xf
	v_fmac_f32_dpp v118, v70, v230 row_shr:2 row_mask:0xf bank_mask:0xf
	v_fmac_f32_dpp v119, v71, v231 row_shr:2 row_mask:0xf bank_mask:0xf
	v_fmac_f32_dpp v120, v72, v232 row_shr:2 row_mask:0xf bank_mask:0xf
	v_fmac_f32_dpp v121, v73, v233 row_shr:2 row_mask:0xf bank_mask:0xf
	v_fmac_f32_dpp v122, v66, v246 row_shr:2 row_mask:0xf bank_mask:0xf
	v_fmac_f32_dpp v123, v67, v247 row_shr:2 row_mask:0xf bank_mask:0xf
	v_fmac_f32_dpp v124, v68, v248 row_shr:2 row_mask:0xf bank_mask:0xf
	v_fmac_f32_dpp v125, v69, v249 row_shr:2 row_mask:0xf bank_mask:0xf
	v_fmac_f32_dpp v118, v78, v226 row_shl:15 row_mask:0xf bank_mask:0xf
	v_fmac_f32_dpp v119, v79, v227 row_shl:15 row_mask:0xf bank_mask:0xf
	v_fmac_f32_dpp v120, v80, v228 row_shl:15 row_mask:0xf bank_mask:0xf
	v_fmac_f32_dpp v121, v81, v229 row_shl:15 row_mask:0xf bank_mask:0xf
	v_fmac_f32_dpp v122, v74, v242 row_shl:15 row_mask:0xf bank_mask:0xf
	v_fmac_f32_dpp v123, v75, v243 row_shl:15 row_mask:0xf bank_mask:0xf
	v_fmac_f32_dpp v124, v76, v244 row_shl:15 row_mask:0xf bank_mask:0xf
	v_fmac_f32_dpp v125, v77, v245 row_shl:15 row_mask:0xf bank_mask:0xf
	v_fmac_f32_dpp v118, v78, v230 row_shl:14 row_mask:0xf bank_mask:0xf
; __device__ __forceinline__ unsigned cvt_pk_bf16(float lo, float hi) { unsigned r; asm volatile("v_cvt_pk_bf16_f32 %0, %1, %2" : "=v"(r) : "v"(lo), "v"(hi)); return r; }
; __device__ __forceinline__ f32x4 gelu4(f32x4 v) { return (f32x4){gelu_t(v[0]), gelu_t(v[1]), gelu_t(v[2]), gelu_t(v[3])}; }
; template <int CTRL> __device__ __forceinline__ f32x4 dpp4(f32x4 v) { return (f32x4){dpp_f<CTRL>(v[0]), dpp_f<CTRL>(v[1]), dpp_f<CTRL>(v[2]), dpp_f<CTRL>(v[3])}; }
;     __device__ __forceinline__ void operator()(const f32x4 (&acc)[2][2][4][2], const Unit& u, int wr, int wc, int fr, int fq) const {
;     ...
;                 const f32x4 wg0 = *(const f32x4*)(bias + c), wg1 = *(const f32x4*)(bias + NUPc + c), wg2 = *(const f32x4*)(bias + 2 * NUPc + c), bg = *(const f32x4*)(xin + c);
;                 const f32x4 wv0 = *(const f32x4*)(bias + DFFc + c), wv1 = *(const f32x4*)(bias + NUPc + DFFc + c), wv2 = *(const f32x4*)(bias + 2 * NUPc + DFFc + c), bv = *(const f32x4*)(xin + DFFc + c);
;     ...
;                     for (int m = 0; m < 4; ++m) {
;                         const f32x4 g = acc[ai][0][m][n] * rs[ai][m], v = acc[ai][1][m][n] * rs[ai][m];
;                         const f32x4 g1 = dpp4<0x121>(g), g2 = dpp4<0x122>(g), v1 = dpp4<0x121>(v), v2 = dpp4<0x122>(v);
;                         const f32x4 gp1 = (fr >= 1) ? g1 : pg1, gp2 = (fr >= 2) ? g2 : pg2, vp1 = (fr >= 1) ? v1 : pv1, vp2 = (fr >= 2) ? v2 : pv2;
;                         const f32x4 cgt = bg + wg0 * g + wg1 * gp1 + wg2 * gp2, cvl = bv + wv0 * v + wv1 * vp1 + wv2 * vp2;
;                         const f32x4 o = gelu4(cgt) * cvl;
;                         typedef unsigned u32x2e __attribute__((ext_vector_type(2)));
;                         u32x2e w; w.x = cvt_pk_bf16(o[0], o[1]); w.y = cvt_pk_bf16(o[2], o[3]);
;                         if (!(m == 0 && fr < 2)) *(u32x2e*)((bf16_t*)O + (size_t)(row0 + ai * HALF + m * 16) * DFFc + c) = w;
;                         pg1 = g1; pg2 = g2; pv1 = v1; pv2 = v2;
	v_fmac_f32_dpp v119, v79, v231 row_shl:14 row_mask:0xf bank_mask:0xf
	v_fmac_f32_dpp v120, v80, v232 row_shl:14 row_mask:0xf bank_mask:0xf
	v_fmac_f32_dpp v121, v81, v233 row_shl:14 row_mask:0xf bank_mask:0xf
	v_fmac_f32_dpp v122, v74, v246 row_shl:14 row_mask:0xf bank_mask:0xf
	v_fmac_f32_dpp v123, v75, v247 row_shl:14 row_mask:0xf bank_mask:0xf
	v_fmac_f32_dpp v124, v76, v248 row_shl:14 row_mask:0xf bank_mask:0xf
	v_fmac_f32_dpp v125, v77, v249 row_shl:14 row_mask:0xf bank_mask:0xf
	v_pk_mul_f32 v[126:127], v[118:119], v[118:119]
	v_pk_mul_f32 v[128:129], v[120:121], v[120:121]
	v_pk_fma_f32 v[126:127], v[126:127], v[132:133], v[196:197] op_sel_hi:[1,0,0]
	v_pk_fma_f32 v[128:129], v[128:129], v[132:133], v[196:197] op_sel_hi:[1,0,0]
	v_pk_mul_f32 v[126:127], v[118:119], v[126:127]
	v_pk_mul_f32 v[128:129], v[120:121], v[128:129]
	v_exp_f32_e32 v126, v126
	v_exp_f32_e32 v127, v127
	v_exp_f32_e32 v128, v128
	v_exp_f32_e32 v129, v129
	v_pk_add_f32 v[126:127], v[126:127], v[250:251] op_sel_hi:[1,0]
	v_pk_add_f32 v[128:129], v[128:129], v[250:251] op_sel_hi:[1,0]
	v_rcp_f32_e32 v126, v126
	v_rcp_f32_e32 v127, v127
	v_rcp_f32_e32 v128, v128
	v_rcp_f32_e32 v129, v129
	v_pk_mul_f32 v[126:127], v[118:119], v[126:127]
	v_pk_mul_f32 v[128:129], v[120:121], v[128:129]
	v_pk_mul_f32 v[126:127], v[122:123], v[126:127]
	v_pk_mul_f32 v[128:129], v[124:125], v[128:129]
	v_cvt_pk_bf16_f32 v126, v126, v127
	v_cvt_pk_bf16_f32 v127, v128, v129
	v_add_u32_e32 v131, 0x1e4000, v199
	global_store_dwordx2 v131, v[126:127], s[68:69]
	s_waitcnt vmcnt(4)
	v_pk_mul_f32 v[62:63], v[62:63], v[188:189] op_sel_hi:[1,0]
	v_pk_mul_f32 v[64:65], v[64:65], v[188:189] op_sel_hi:[1,0]
	v_pk_mul_f32 v[58:59], v[58:59], v[188:189] op_sel_hi:[1,0]
	v_pk_mul_f32 v[60:61], v[60:61], v[188:189] op_sel_hi:[1,0]
	v_pk_fma_f32 v[106:107], v[62:63], v[154:155], v[150:151]
	v_pk_fma_f32 v[108:109], v[64:65], v[156:157], v[152:153]
	v_pk_fma_f32 v[110:111], v[58:59], v[134:135], v[146:147]
	v_pk_fma_f32 v[112:113], v[60:61], v[136:137], v[148:149]
	v_fmac_f32_dpp v106, v62, v142 row_shr:1 row_mask:0xf bank_mask:0xf
	v_fmac_f32_dpp v107, v63, v143 row_shr:1 row_mask:0xf bank_mask:0xf
	v_fmac_f32_dpp v108, v64, v144 row_shr:1 row_mask:0xf bank_mask:0xf
	v_fmac_f32_dpp v109, v65, v145 row_shr:1 row_mask:0xf bank_mask:0xf
	v_fmac_f32_dpp v110, v58, v138 row_shr:1 row_mask:0xf bank_mask:0xf
	v_fmac_f32_dpp v111, v59, v139 row_shr:1 row_mask:0xf bank_mask:0xf
	v_fmac_f32_dpp v112, v60, v140 row_shr:1 row_mask:0xf bank_mask:0xf
	v_fmac_f32_dpp v113, v61, v141 row_shr:1 row_mask:0xf bank_mask:0xf
	v_fmac_f32_dpp v106, v62, v102 row_shr:2 row_mask:0xf bank_mask:0xf
	v_fmac_f32_dpp v107, v63, v103 row_shr:2 row_mask:0xf bank_mask:0xf
	v_fmac_f32_dpp v108, v64, v104 row_shr:2 row_mask:0xf bank_mask:0xf
	v_fmac_f32_dpp v109, v65, v105 row_shr:2 row_mask:0xf bank_mask:0xf
	v_fmac_f32_dpp v110, v58, v98 row_shr:2 row_mask:0xf bank_mask:0xf
	v_fmac_f32_dpp v111, v59, v99 row_shr:2 row_mask:0xf bank_mask:0xf
	v_fmac_f32_dpp v112, v60, v100 row_shr:2 row_mask:0xf bank_mask:0xf
	v_fmac_f32_dpp v113, v61, v101 row_shr:2 row_mask:0xf bank_mask:0xf
	v_pk_mul_f32 v[114:115], v[106:107], v[106:107]
	v_pk_mul_f32 v[116:117], v[108:109], v[108:109]
	v_pk_fma_f32 v[114:115], v[114:115], v[132:133], v[196:197] op_sel_hi:[1,0,0]
	v_pk_fma_f32 v[116:117], v[116:117], v[132:133], v[196:197] op_sel_hi:[1,0,0]
	v_pk_mul_f32 v[114:115], v[106:107], v[114:115]
	v_pk_mul_f32 v[116:117], v[108:109], v[116:117]
	v_exp_f32_e32 v114, v114
	v_exp_f32_e32 v115, v115
	v_exp_f32_e32 v116, v116
	v_exp_f32_e32 v117, v117
	v_pk_add_f32 v[114:115], v[114:115], v[250:251] op_sel_hi:[1,0]
	v_pk_add_f32 v[116:117], v[116:117], v[250:251] op_sel_hi:[1,0]
	v_rcp_f32_e32 v114, v114
	v_rcp_f32_e32 v115, v115
	v_rcp_f32_e32 v116, v116
	v_rcp_f32_e32 v117, v117
	v_pk_mul_f32 v[114:115], v[106:107], v[114:115]
	v_pk_mul_f32 v[116:117], v[108:109], v[116:117]
	v_pk_mul_f32 v[114:115], v[110:111], v[114:115]
	v_pk_mul_f32 v[116:117], v[112:113], v[116:117]
	v_cvt_pk_bf16_f32 v114, v114, v115
	v_cvt_pk_bf16_f32 v115, v116, v117
	s_and_saveexec_b64 s[48:49], s[10:11]
	global_store_dwordx2 v199, v[114:115], s[68:69] offset:8
	s_or_b64 exec, exec, s[48:49]
	v_pk_mul_f32 v[54:55], v[54:55], v[190:191] op_sel_hi:[1,0]
	v_pk_mul_f32 v[56:57], v[56:57], v[190:191] op_sel_hi:[1,0]
	v_pk_mul_f32 v[50:51], v[50:51], v[190:191] op_sel_hi:[1,0]
	v_pk_mul_f32 v[52:53], v[52:53], v[190:191] op_sel_hi:[1,0]
	v_pk_fma_f32 v[118:119], v[54:55], v[154:155], v[150:151]
	v_pk_fma_f32 v[120:121], v[56:57], v[156:157], v[152:153]
	v_pk_fma_f32 v[122:123], v[50:51], v[134:135], v[146:147]
	v_pk_fma_f32 v[124:125], v[52:53], v[136:137], v[148:149]
	v_fmac_f32_dpp v118, v54, v142 row_shr:1 row_mask:0xf bank_mask:0xf
	v_fmac_f32_dpp v119, v55, v143 row_shr:1 row_mask:0xf bank_mask:0xf
	v_fmac_f32_dpp v120, v56, v144 row_shr:1 row_mask:0xf bank_mask:0xf
	v_fmac_f32_dpp v121, v57, v145 row_shr:1 row_mask:0xf bank_mask:0xf
	v_fmac_f32_dpp v122, v50, v138 row_shr:1 row_mask:0xf bank_mask:0xf
	v_fmac_f32_dpp v123, v51, v139 row_shr:1 row_mask:0xf bank_mask:0xf
	v_fmac_f32_dpp v124, v52, v140 row_shr:1 row_mask:0xf bank_mask:0xf
	v_fmac_f32_dpp v125, v53, v141 row_shr:1 row_mask:0xf bank_mask:0xf
	v_fmac_f32_dpp v118, v54, v102 row_shr:2 row_mask:0xf bank_mask:0xf
	v_fmac_f32_dpp v119, v55, v103 row_shr:2 row_mask:0xf bank_mask:0xf
	v_fmac_f32_dpp v120, v56, v104 row_shr:2 row_mask:0xf bank_mask:0xf
	v_fmac_f32_dpp v121, v57, v105 row_shr:2 row_mask:0xf bank_mask:0xf
	v_fmac_f32_dpp v122, v50, v98 row_shr:2 row_mask:0xf bank_mask:0xf
	v_fmac_f32_dpp v123, v51, v99 row_shr:2 row_mask:0xf bank_mask:0xf
; __device__ __forceinline__ unsigned cvt_pk_bf16(float lo, float hi) { unsigned r; asm volatile("v_cvt_pk_bf16_f32 %0, %1, %2" : "=v"(r) : "v"(lo), "v"(hi)); return r; }
; __device__ __forceinline__ f32x4 gelu4(f32x4 v) { return (f32x4){gelu_t(v[0]), gelu_t(v[1]), gelu_t(v[2]), gelu_t(v[3])}; }
; template <int CTRL> __device__ __forceinline__ f32x4 dpp4(f32x4 v) { return (f32x4){dpp_f<CTRL>(v[0]), dpp_f<CTRL>(v[1]), dpp_f<CTRL>(v[2]), dpp_f<CTRL>(v[3])}; }
;     __device__ __forceinline__ void operator()(const f32x4 (&acc)[2][2][4][2], const Unit& u, int wr, int wc, int fr, int fq) const {
;     ...
;                         const f32x4 g = acc[ai][0][m][n] * rs[ai][m], v = acc[ai][1][m][n] * rs[ai][m];
;                         const f32x4 g1 = dpp4<0x121>(g), g2 = dpp4<0x122>(g), v1 = dpp4<0x121>(v), v2 = dpp4<0x122>(v);
;                         const f32x4 gp1 = (fr >= 1) ? g1 : pg1, gp2 = (fr >= 2) ? g2 : pg2, vp1 = (fr >= 1) ? v1 : pv1, vp2 = (fr >= 2) ? v2 : pv2;
;                         const f32x4 cgt = bg + wg0 * g + wg1 * gp1 + wg2 * gp2, cvl = bv + wv0 * v + wv1 * vp1 + wv2 * vp2;
;                         const f32x4 o = gelu4(cgt) * cvl;
;                         typedef unsigned u32x2e __attribute__((ext_vector_type(2)));
;                         u32x2e w; w.x = cvt_pk_bf16(o[0], o[1]); w.y = cvt_pk_bf16(o[2], o[3]);
;                         if (!(m == 0 && fr < 2)) *(u32x2e*)((bf16_t*)O + (size_t)(row0 + ai * HALF + m * 16) * DFFc + c) = w;
;                         pg1 = g1; pg2 = g2; pv1 = v1; pv2 = v2;
	v_fmac_f32_dpp v124, v52, v100 row_shr:2 row_mask:0xf bank_mask:0xf
	v_fmac_f32_dpp v125, v53, v101 row_shr:2 row_mask:0xf bank_mask:0xf
	v_fmac_f32_dpp v118, v62, v142 row_shl:15 row_mask:0xf bank_mask:0xf
	v_fmac_f32_dpp v119, v63, v143 row_shl:15 row_mask:0xf bank_mask:0xf
	v_fmac_f32_dpp v120, v64, v144 row_shl:15 row_mask:0xf bank_mask:0xf
	v_fmac_f32_dpp v121, v65, v145 row_shl:15 row_mask:0xf bank_mask:0xf
	v_fmac_f32_dpp v122, v58, v138 row_shl:15 row_mask:0xf bank_mask:0xf
	v_fmac_f32_dpp v123, v59, v139 row_shl:15 row_mask:0xf bank_mask:0xf
	v_fmac_f32_dpp v124, v60, v140 row_shl:15 row_mask:0xf bank_mask:0xf
	v_fmac_f32_dpp v125, v61, v141 row_shl:15 row_mask:0xf bank_mask:0xf
	v_fmac_f32_dpp v118, v62, v102 row_shl:14 row_mask:0xf bank_mask:0xf
	v_fmac_f32_dpp v119, v63, v103 row_shl:14 row_mask:0xf bank_mask:0xf
	v_fmac_f32_dpp v120, v64, v104 row_shl:14 row_mask:0xf bank_mask:0xf
	v_fmac_f32_dpp v121, v65, v105 row_shl:14 row_mask:0xf bank_mask:0xf
	v_fmac_f32_dpp v122, v58, v98 row_shl:14 row_mask:0xf bank_mask:0xf
	v_fmac_f32_dpp v123, v59, v99 row_shl:14 row_mask:0xf bank_mask:0xf
	v_fmac_f32_dpp v124, v60, v100 row_shl:14 row_mask:0xf bank_mask:0xf
	v_fmac_f32_dpp v125, v61, v101 row_shl:14 row_mask:0xf bank_mask:0xf
	v_pk_mul_f32 v[126:127], v[118:119], v[118:119]
	v_pk_mul_f32 v[128:129], v[120:121], v[120:121]
	v_pk_fma_f32 v[126:127], v[126:127], v[132:133], v[196:197] op_sel_hi:[1,0,0]
	v_pk_fma_f32 v[128:129], v[128:129], v[132:133], v[196:197] op_sel_hi:[1,0,0]
	v_pk_mul_f32 v[126:127], v[118:119], v[126:127]
	v_pk_mul_f32 v[128:129], v[120:121], v[128:129]
	v_exp_f32_e32 v126, v126
	v_exp_f32_e32 v127, v127
	v_exp_f32_e32 v128, v128
	v_exp_f32_e32 v129, v129
	v_pk_add_f32 v[126:127], v[126:127], v[250:251] op_sel_hi:[1,0]
	v_pk_add_f32 v[128:129], v[128:129], v[250:251] op_sel_hi:[1,0]
	v_rcp_f32_e32 v126, v126
	v_rcp_f32_e32 v127, v127
	v_rcp_f32_e32 v128, v128
	v_rcp_f32_e32 v129, v129
	v_pk_mul_f32 v[126:127], v[118:119], v[126:127]
	v_pk_mul_f32 v[128:129], v[120:121], v[128:129]
	v_pk_mul_f32 v[126:127], v[122:123], v[126:127]
	v_pk_mul_f32 v[128:129], v[124:125], v[128:129]
	v_cvt_pk_bf16_f32 v126, v126, v127
	v_cvt_pk_bf16_f32 v127, v128, v129
	v_add_u32_e32 v131, 0x2c000, v199
	global_store_dwordx2 v131, v[126:127], s[68:69] offset:8
	v_pk_mul_f32 v[46:47], v[46:47], v[192:193] op_sel_hi:[1,0]
	v_pk_mul_f32 v[48:49], v[48:49], v[192:193] op_sel_hi:[1,0]
	v_pk_mul_f32 v[42:43], v[42:43], v[192:193] op_sel_hi:[1,0]
	v_pk_mul_f32 v[44:45], v[44:45], v[192:193] op_sel_hi:[1,0]
	v_pk_fma_f32 v[106:107], v[46:47], v[154:155], v[150:151]
	v_pk_fma_f32 v[108:109], v[48:49], v[156:157], v[152:153]
	v_pk_fma_f32 v[110:111], v[42:43], v[134:135], v[146:147]
	v_pk_fma_f32 v[112:113], v[44:45], v[136:137], v[148:149]
	v_fmac_f32_dpp v106, v46, v142 row_shr:1 row_mask:0xf bank_mask:0xf
	v_fmac_f32_dpp v107, v47, v143 row_shr:1 row_mask:0xf bank_mask:0xf
	v_fmac_f32_dpp v108, v48, v144 row_shr:1 row_mask:0xf bank_mask:0xf
	v_fmac_f32_dpp v109, v49, v145 row_shr:1 row_mask:0xf bank_mask:0xf
	v_fmac_f32_dpp v110, v42, v138 row_shr:1 row_mask:0xf bank_mask:0xf
	v_fmac_f32_dpp v111, v43, v139 row_shr:1 row_mask:0xf bank_mask:0xf
	v_fmac_f32_dpp v112, v44, v140 row_shr:1 row_mask:0xf bank_mask:0xf
	v_fmac_f32_dpp v113, v45, v141 row_shr:1 row_mask:0xf bank_mask:0xf
	v_fmac_f32_dpp v106, v46, v102 row_shr:2 row_mask:0xf bank_mask:0xf
	v_fmac_f32_dpp v107, v47, v103 row_shr:2 row_mask:0xf bank_mask:0xf
	v_fmac_f32_dpp v108, v48, v104 row_shr:2 row_mask:0xf bank_mask:0xf
	v_fmac_f32_dpp v109, v49, v105 row_shr:2 row_mask:0xf bank_mask:0xf
	v_fmac_f32_dpp v110, v42, v98 row_shr:2 row_mask:0xf bank_mask:0xf
	v_fmac_f32_dpp v111, v43, v99 row_shr:2 row_mask:0xf bank_mask:0xf
	v_fmac_f32_dpp v112, v44, v100 row_shr:2 row_mask:0xf bank_mask:0xf
	v_fmac_f32_dpp v113, v45, v101 row_shr:2 row_mask:0xf bank_mask:0xf
	v_fmac_f32_dpp v106, v54, v142 row_shl:15 row_mask:0xf bank_mask:0xf
	v_fmac_f32_dpp v107, v55, v143 row_shl:15 row_mask:0xf bank_mask:0xf
	v_fmac_f32_dpp v108, v56, v144 row_shl:15 row_mask:0xf bank_mask:0xf
	v_fmac_f32_dpp v109, v57, v145 row_shl:15 row_mask:0xf bank_mask:0xf
	v_fmac_f32_dpp v110, v50, v138 row_shl:15 row_mask:0xf bank_mask:0xf
	v_fmac_f32_dpp v111, v51, v139 row_shl:15 row_mask:0xf bank_mask:0xf
	v_fmac_f32_dpp v112, v52, v140 row_shl:15 row_mask:0xf bank_mask:0xf
	v_fmac_f32_dpp v113, v53, v141 row_shl:15 row_mask:0xf bank_mask:0xf
	v_fmac_f32_dpp v106, v54, v102 row_shl:14 row_mask:0xf bank_mask:0xf
	v_fmac_f32_dpp v107, v55, v103 row_shl:14 row_mask:0xf bank_mask:0xf
	v_fmac_f32_dpp v108, v56, v104 row_shl:14 row_mask:0xf bank_mask:0xf
	v_fmac_f32_dpp v109, v57, v105 row_shl:14 row_mask:0xf bank_mask:0xf
	v_fmac_f32_dpp v110, v50, v98 row_shl:14 row_mask:0xf bank_mask:0xf
	v_fmac_f32_dpp v111, v51, v99 row_shl:14 row_mask:0xf bank_mask:0xf
	v_fmac_f32_dpp v112, v52, v100 row_shl:14 row_mask:0xf bank_mask:0xf
	v_fmac_f32_dpp v113, v53, v101 row_shl:14 row_mask:0xf bank_mask:0xf
	v_pk_mul_f32 v[114:115], v[106:107], v[106:107]
	v_pk_mul_f32 v[116:117], v[108:109], v[108:109]
	v_pk_fma_f32 v[114:115], v[114:115], v[132:133], v[196:197] op_sel_hi:[1,0,0]
	v_pk_fma_f32 v[116:117], v[116:117], v[132:133], v[196:197] op_sel_hi:[1,0,0]
	v_pk_mul_f32 v[114:115], v[106:107], v[114:115]
	v_pk_mul_f32 v[116:117], v[108:109], v[116:117]
	v_exp_f32_e32 v114, v114
	v_exp_f32_e32 v115, v115
	v_exp_f32_e32 v116, v116
	v_exp_f32_e32 v117, v117
	v_pk_add_f32 v[114:115], v[114:115], v[250:251] op_sel_hi:[1,0]
	v_pk_add_f32 v[116:117], v[116:117], v[250:251] op_sel_hi:[1,0]
	v_rcp_f32_e32 v114, v114
	v_rcp_f32_e32 v115, v115
; __device__ __forceinline__ unsigned cvt_pk_bf16(float lo, float hi) { unsigned r; asm volatile("v_cvt_pk_bf16_f32 %0, %1, %2" : "=v"(r) : "v"(lo), "v"(hi)); return r; }
; __device__ __forceinline__ f32x4 gelu4(f32x4 v) { return (f32x4){gelu_t(v[0]), gelu_t(v[1]), gelu_t(v[2]), gelu_t(v[3])}; }
; template <int CTRL> __device__ __forceinline__ f32x4 dpp4(f32x4 v) { return (f32x4){dpp_f<CTRL>(v[0]), dpp_f<CTRL>(v[1]), dpp_f<CTRL>(v[2]), dpp_f<CTRL>(v[3])}; }
;     __device__ __forceinline__ void operator()(const f32x4 (&acc)[2][2][4][2], const Unit& u, int wr, int wc, int fr, int fq) const {
;     ...
;                         const f32x4 g = acc[ai][0][m][n] * rs[ai][m], v = acc[ai][1][m][n] * rs[ai][m];
;                         const f32x4 g1 = dpp4<0x121>(g), g2 = dpp4<0x122>(g), v1 = dpp4<0x121>(v), v2 = dpp4<0x122>(v);
;                         const f32x4 gp1 = (fr >= 1) ? g1 : pg1, gp2 = (fr >= 2) ? g2 : pg2, vp1 = (fr >= 1) ? v1 : pv1, vp2 = (fr >= 2) ? v2 : pv2;
;                         const f32x4 cgt = bg + wg0 * g + wg1 * gp1 + wg2 * gp2, cvl = bv + wv0 * v + wv1 * vp1 + wv2 * vp2;
;                         const f32x4 o = gelu4(cgt) * cvl;
;                         typedef unsigned u32x2e __attribute__((ext_vector_type(2)));
;                         u32x2e w; w.x = cvt_pk_bf16(o[0], o[1]); w.y = cvt_pk_bf16(o[2], o[3]);
;                         if (!(m == 0 && fr < 2)) *(u32x2e*)((bf16_t*)O + (size_t)(row0 + ai * HALF + m * 16) * DFFc + c) = w;
;                         pg1 = g1; pg2 = g2; pv1 = v1; pv2 = v2;
	v_rcp_f32_e32 v116, v116
	v_rcp_f32_e32 v117, v117
	v_pk_mul_f32 v[114:115], v[106:107], v[114:115]
	v_pk_mul_f32 v[116:117], v[108:109], v[116:117]
	v_pk_mul_f32 v[114:115], v[110:111], v[114:115]
	v_pk_mul_f32 v[116:117], v[112:113], v[116:117]
	v_cvt_pk_bf16_f32 v114, v114, v115
	v_cvt_pk_bf16_f32 v115, v116, v117
	v_add_u32_e32 v130, 0x58000, v199
	global_store_dwordx2 v130, v[114:115], s[68:69] offset:8
	v_pk_mul_f32 v[38:39], v[38:39], v[184:185] op_sel_hi:[1,0]
	v_pk_mul_f32 v[40:41], v[40:41], v[184:185] op_sel_hi:[1,0]
	v_pk_mul_f32 v[34:35], v[34:35], v[184:185] op_sel_hi:[1,0]
	v_pk_mul_f32 v[36:37], v[36:37], v[184:185] op_sel_hi:[1,0]
	v_pk_fma_f32 v[118:119], v[38:39], v[154:155], v[150:151]
	v_pk_fma_f32 v[120:121], v[40:41], v[156:157], v[152:153]
	v_pk_fma_f32 v[122:123], v[34:35], v[134:135], v[146:147]
	v_pk_fma_f32 v[124:125], v[36:37], v[136:137], v[148:149]
	v_fmac_f32_dpp v118, v38, v142 row_shr:1 row_mask:0xf bank_mask:0xf
	v_fmac_f32_dpp v119, v39, v143 row_shr:1 row_mask:0xf bank_mask:0xf
	v_fmac_f32_dpp v120, v40, v144 row_shr:1 row_mask:0xf bank_mask:0xf
	v_fmac_f32_dpp v121, v41, v145 row_shr:1 row_mask:0xf bank_mask:0xf
	v_fmac_f32_dpp v122, v34, v138 row_shr:1 row_mask:0xf bank_mask:0xf
	v_fmac_f32_dpp v123, v35, v139 row_shr:1 row_mask:0xf bank_mask:0xf
	v_fmac_f32_dpp v124, v36, v140 row_shr:1 row_mask:0xf bank_mask:0xf
	v_fmac_f32_dpp v125, v37, v141 row_shr:1 row_mask:0xf bank_mask:0xf
	v_fmac_f32_dpp v118, v38, v102 row_shr:2 row_mask:0xf bank_mask:0xf
	v_fmac_f32_dpp v119, v39, v103 row_shr:2 row_mask:0xf bank_mask:0xf
	v_fmac_f32_dpp v120, v40, v104 row_shr:2 row_mask:0xf bank_mask:0xf
	v_fmac_f32_dpp v121, v41, v105 row_shr:2 row_mask:0xf bank_mask:0xf
	v_fmac_f32_dpp v122, v34, v98 row_shr:2 row_mask:0xf bank_mask:0xf
	v_fmac_f32_dpp v123, v35, v99 row_shr:2 row_mask:0xf bank_mask:0xf
	v_fmac_f32_dpp v124, v36, v100 row_shr:2 row_mask:0xf bank_mask:0xf
	v_fmac_f32_dpp v125, v37, v101 row_shr:2 row_mask:0xf bank_mask:0xf
	v_fmac_f32_dpp v118, v46, v142 row_shl:15 row_mask:0xf bank_mask:0xf
	v_fmac_f32_dpp v119, v47, v143 row_shl:15 row_mask:0xf bank_mask:0xf
	v_fmac_f32_dpp v120, v48, v144 row_shl:15 row_mask:0xf bank_mask:0xf
	v_fmac_f32_dpp v121, v49, v145 row_shl:15 row_mask:0xf bank_mask:0xf
	v_fmac_f32_dpp v122, v42, v138 row_shl:15 row_mask:0xf bank_mask:0xf
	v_fmac_f32_dpp v123, v43, v139 row_shl:15 row_mask:0xf bank_mask:0xf
	v_fmac_f32_dpp v124, v44, v140 row_shl:15 row_mask:0xf bank_mask:0xf
	v_fmac_f32_dpp v125, v45, v141 row_shl:15 row_mask:0xf bank_mask:0xf
	v_fmac_f32_dpp v118, v46, v102 row_shl:14 row_mask:0xf bank_mask:0xf
	v_fmac_f32_dpp v119, v47, v103 row_shl:14 row_mask:0xf bank_mask:0xf
	v_fmac_f32_dpp v120, v48, v104 row_shl:14 row_mask:0xf bank_mask:0xf
	v_fmac_f32_dpp v121, v49, v105 row_shl:14 row_mask:0xf bank_mask:0xf
	v_fmac_f32_dpp v122, v42, v98 row_shl:14 row_mask:0xf bank_mask:0xf
	v_fmac_f32_dpp v123, v43, v99 row_shl:14 row_mask:0xf bank_mask:0xf
	v_fmac_f32_dpp v124, v44, v100 row_shl:14 row_mask:0xf bank_mask:0xf
	v_fmac_f32_dpp v125, v45, v101 row_shl:14 row_mask:0xf bank_mask:0xf
	v_pk_mul_f32 v[126:127], v[118:119], v[118:119]
	v_pk_mul_f32 v[128:129], v[120:121], v[120:121]
	v_pk_fma_f32 v[126:127], v[126:127], v[132:133], v[196:197] op_sel_hi:[1,0,0]
	v_pk_fma_f32 v[128:129], v[128:129], v[132:133], v[196:197] op_sel_hi:[1,0,0]
	v_pk_mul_f32 v[126:127], v[118:119], v[126:127]
	v_pk_mul_f32 v[128:129], v[120:121], v[128:129]
	v_exp_f32_e32 v126, v126
	v_exp_f32_e32 v127, v127
	v_exp_f32_e32 v128, v128
	v_exp_f32_e32 v129, v129
	v_pk_add_f32 v[126:127], v[126:127], v[250:251] op_sel_hi:[1,0]
	v_pk_add_f32 v[128:129], v[128:129], v[250:251] op_sel_hi:[1,0]
	v_rcp_f32_e32 v126, v126
	v_rcp_f32_e32 v127, v127
	v_rcp_f32_e32 v128, v128
	v_rcp_f32_e32 v129, v129
	v_pk_mul_f32 v[126:127], v[118:119], v[126:127]
	v_pk_mul_f32 v[128:129], v[120:121], v[128:129]
	v_pk_mul_f32 v[126:127], v[122:123], v[126:127]
	v_pk_mul_f32 v[128:129], v[124:125], v[128:129]
	v_cvt_pk_bf16_f32 v126, v126, v127
	v_cvt_pk_bf16_f32 v127, v128, v129
	v_add_u32_e32 v131, 0x84000, v199
	global_store_dwordx2 v131, v[126:127], s[68:69] offset:8
	v_pk_mul_f32 v[30:31], v[30:31], v[182:183] op_sel_hi:[1,0]
	v_pk_mul_f32 v[32:33], v[32:33], v[182:183] op_sel_hi:[1,0]
	v_pk_mul_f32 v[26:27], v[26:27], v[182:183] op_sel_hi:[1,0]
	v_pk_mul_f32 v[28:29], v[28:29], v[182:183] op_sel_hi:[1,0]
	v_pk_fma_f32 v[106:107], v[30:31], v[154:155], v[150:151]
	v_pk_fma_f32 v[108:109], v[32:33], v[156:157], v[152:153]
	v_pk_fma_f32 v[110:111], v[26:27], v[134:135], v[146:147]
	v_pk_fma_f32 v[112:113], v[28:29], v[136:137], v[148:149]
	v_fmac_f32_dpp v106, v30, v142 row_shr:1 row_mask:0xf bank_mask:0xf
	v_fmac_f32_dpp v107, v31, v143 row_shr:1 row_mask:0xf bank_mask:0xf
	v_fmac_f32_dpp v108, v32, v144 row_shr:1 row_mask:0xf bank_mask:0xf
	v_fmac_f32_dpp v109, v33, v145 row_shr:1 row_mask:0xf bank_mask:0xf
	v_fmac_f32_dpp v110, v26, v138 row_shr:1 row_mask:0xf bank_mask:0xf
	v_fmac_f32_dpp v111, v27, v139 row_shr:1 row_mask:0xf bank_mask:0xf
	v_fmac_f32_dpp v112, v28, v140 row_shr:1 row_mask:0xf bank_mask:0xf
	v_fmac_f32_dpp v113, v29, v141 row_shr:1 row_mask:0xf bank_mask:0xf
	v_fmac_f32_dpp v106, v30, v102 row_shr:2 row_mask:0xf bank_mask:0xf
	v_fmac_f32_dpp v107, v31, v103 row_shr:2 row_mask:0xf bank_mask:0xf
	v_fmac_f32_dpp v108, v32, v104 row_shr:2 row_mask:0xf bank_mask:0xf
	v_fmac_f32_dpp v109, v33, v105 row_shr:2 row_mask:0xf bank_mask:0xf
	v_fmac_f32_dpp v110, v26, v98 row_shr:2 row_mask:0xf bank_mask:0xf
	v_fmac_f32_dpp v111, v27, v99 row_shr:2 row_mask:0xf bank_mask:0xf
; __device__ __forceinline__ unsigned cvt_pk_bf16(float lo, float hi) { unsigned r; asm volatile("v_cvt_pk_bf16_f32 %0, %1, %2" : "=v"(r) : "v"(lo), "v"(hi)); return r; }
; __device__ __forceinline__ f32x4 gelu4(f32x4 v) { return (f32x4){gelu_t(v[0]), gelu_t(v[1]), gelu_t(v[2]), gelu_t(v[3])}; }
; template <int CTRL> __device__ __forceinline__ f32x4 dpp4(f32x4 v) { return (f32x4){dpp_f<CTRL>(v[0]), dpp_f<CTRL>(v[1]), dpp_f<CTRL>(v[2]), dpp_f<CTRL>(v[3])}; }
;     __device__ __forceinline__ void operator()(const f32x4 (&acc)[2][2][4][2], const Unit& u, int wr, int wc, int fr, int fq) const {
;     ...
;                 for (int ai = 0; ai < 2; ++ai) {
;                     f32x4 pg1 = (f32x4){0.f, 0.f, 0.f, 0.f}, pg2 = pg1, pv1 = pg1, pv2 = pg1;
; #pragma unroll
;                     for (int m = 0; m < 4; ++m) {
;                         const f32x4 g = acc[ai][0][m][n] * rs[ai][m], v = acc[ai][1][m][n] * rs[ai][m];
;                         const f32x4 g1 = dpp4<0x121>(g), g2 = dpp4<0x122>(g), v1 = dpp4<0x121>(v), v2 = dpp4<0x122>(v);
;                         const f32x4 gp1 = (fr >= 1) ? g1 : pg1, gp2 = (fr >= 2) ? g2 : pg2, vp1 = (fr >= 1) ? v1 : pv1, vp2 = (fr >= 2) ? v2 : pv2;
;                         const f32x4 cgt = bg + wg0 * g + wg1 * gp1 + wg2 * gp2, cvl = bv + wv0 * v + wv1 * vp1 + wv2 * vp2;
;                         const f32x4 o = gelu4(cgt) * cvl;
;                         typedef unsigned u32x2e __attribute__((ext_vector_type(2)));
;                         u32x2e w; w.x = cvt_pk_bf16(o[0], o[1]); w.y = cvt_pk_bf16(o[2], o[3]);
;                         if (!(m == 0 && fr < 2)) *(u32x2e*)((bf16_t*)O + (size_t)(row0 + ai * HALF + m * 16) * DFFc + c) = w;
;                         pg1 = g1; pg2 = g2; pv1 = v1; pv2 = v2;
	v_fmac_f32_dpp v112, v28, v100 row_shr:2 row_mask:0xf bank_mask:0xf
	v_fmac_f32_dpp v113, v29, v101 row_shr:2 row_mask:0xf bank_mask:0xf
	v_pk_mul_f32 v[114:115], v[106:107], v[106:107]
	v_pk_mul_f32 v[116:117], v[108:109], v[108:109]
	v_pk_fma_f32 v[114:115], v[114:115], v[132:133], v[196:197] op_sel_hi:[1,0,0]
	v_pk_fma_f32 v[116:117], v[116:117], v[132:133], v[196:197] op_sel_hi:[1,0,0]
	v_pk_mul_f32 v[114:115], v[106:107], v[114:115]
	v_pk_mul_f32 v[116:117], v[108:109], v[116:117]
	v_exp_f32_e32 v114, v114
	v_exp_f32_e32 v115, v115
	v_exp_f32_e32 v116, v116
	v_exp_f32_e32 v117, v117
	v_pk_add_f32 v[114:115], v[114:115], v[250:251] op_sel_hi:[1,0]
	v_pk_add_f32 v[116:117], v[116:117], v[250:251] op_sel_hi:[1,0]
	v_rcp_f32_e32 v114, v114
	v_rcp_f32_e32 v115, v115
	v_rcp_f32_e32 v116, v116
	v_rcp_f32_e32 v117, v117
	v_pk_mul_f32 v[114:115], v[106:107], v[114:115]
	v_pk_mul_f32 v[116:117], v[108:109], v[116:117]
	v_pk_mul_f32 v[114:115], v[110:111], v[114:115]
	v_pk_mul_f32 v[116:117], v[112:113], v[116:117]
	v_cvt_pk_bf16_f32 v114, v114, v115
	v_cvt_pk_bf16_f32 v115, v116, v117
	v_add_u32_e32 v130, 0x160000, v199
	s_and_saveexec_b64 s[48:49], s[10:11]
	global_store_dwordx2 v130, v[114:115], s[68:69] offset:8
	s_or_b64 exec, exec, s[48:49]
	v_pk_mul_f32 v[22:23], v[22:23], v[180:181] op_sel_hi:[1,0]
	v_pk_mul_f32 v[24:25], v[24:25], v[180:181] op_sel_hi:[1,0]
	v_pk_mul_f32 v[18:19], v[18:19], v[180:181] op_sel_hi:[1,0]
	v_pk_mul_f32 v[20:21], v[20:21], v[180:181] op_sel_hi:[1,0]
	v_pk_fma_f32 v[118:119], v[22:23], v[154:155], v[150:151]
	v_pk_fma_f32 v[120:121], v[24:25], v[156:157], v[152:153]
	v_pk_fma_f32 v[122:123], v[18:19], v[134:135], v[146:147]
	v_pk_fma_f32 v[124:125], v[20:21], v[136:137], v[148:149]
	v_fmac_f32_dpp v118, v22, v142 row_shr:1 row_mask:0xf bank_mask:0xf
	v_fmac_f32_dpp v119, v23, v143 row_shr:1 row_mask:0xf bank_mask:0xf
	v_fmac_f32_dpp v120, v24, v144 row_shr:1 row_mask:0xf bank_mask:0xf
	v_fmac_f32_dpp v121, v25, v145 row_shr:1 row_mask:0xf bank_mask:0xf
	v_fmac_f32_dpp v122, v18, v138 row_shr:1 row_mask:0xf bank_mask:0xf
	v_fmac_f32_dpp v123, v19, v139 row_shr:1 row_mask:0xf bank_mask:0xf
	v_fmac_f32_dpp v124, v20, v140 row_shr:1 row_mask:0xf bank_mask:0xf
	v_fmac_f32_dpp v125, v21, v141 row_shr:1 row_mask:0xf bank_mask:0xf
	v_fmac_f32_dpp v118, v22, v102 row_shr:2 row_mask:0xf bank_mask:0xf
	v_fmac_f32_dpp v119, v23, v103 row_shr:2 row_mask:0xf bank_mask:0xf
	v_fmac_f32_dpp v120, v24, v104 row_shr:2 row_mask:0xf bank_mask:0xf
	v_fmac_f32_dpp v121, v25, v105 row_shr:2 row_mask:0xf bank_mask:0xf
	v_fmac_f32_dpp v122, v18, v98 row_shr:2 row_mask:0xf bank_mask:0xf
	v_fmac_f32_dpp v123, v19, v99 row_shr:2 row_mask:0xf bank_mask:0xf
	v_fmac_f32_dpp v124, v20, v100 row_shr:2 row_mask:0xf bank_mask:0xf
	v_fmac_f32_dpp v125, v21, v101 row_shr:2 row_mask:0xf bank_mask:0xf
	v_fmac_f32_dpp v118, v30, v142 row_shl:15 row_mask:0xf bank_mask:0xf
	v_fmac_f32_dpp v119, v31, v143 row_shl:15 row_mask:0xf bank_mask:0xf
	v_fmac_f32_dpp v120, v32, v144 row_shl:15 row_mask:0xf bank_mask:0xf
	v_fmac_f32_dpp v121, v33, v145 row_shl:15 row_mask:0xf bank_mask:0xf
	v_fmac_f32_dpp v122, v26, v138 row_shl:15 row_mask:0xf bank_mask:0xf
	v_fmac_f32_dpp v123, v27, v139 row_shl:15 row_mask:0xf bank_mask:0xf
	v_fmac_f32_dpp v124, v28, v140 row_shl:15 row_mask:0xf bank_mask:0xf
	v_fmac_f32_dpp v125, v29, v141 row_shl:15 row_mask:0xf bank_mask:0xf
	v_fmac_f32_dpp v118, v30, v102 row_shl:14 row_mask:0xf bank_mask:0xf
	v_fmac_f32_dpp v119, v31, v103 row_shl:14 row_mask:0xf bank_mask:0xf
	v_fmac_f32_dpp v120, v32, v104 row_shl:14 row_mask:0xf bank_mask:0xf
	v_fmac_f32_dpp v121, v33, v105 row_shl:14 row_mask:0xf bank_mask:0xf
	v_fmac_f32_dpp v122, v26, v98 row_shl:14 row_mask:0xf bank_mask:0xf
	v_fmac_f32_dpp v123, v27, v99 row_shl:14 row_mask:0xf bank_mask:0xf
	v_fmac_f32_dpp v124, v28, v100 row_shl:14 row_mask:0xf bank_mask:0xf
	v_fmac_f32_dpp v125, v29, v101 row_shl:14 row_mask:0xf bank_mask:0xf
	v_pk_mul_f32 v[126:127], v[118:119], v[118:119]
	v_pk_mul_f32 v[128:129], v[120:121], v[120:121]
	v_pk_fma_f32 v[126:127], v[126:127], v[132:133], v[196:197] op_sel_hi:[1,0,0]
	v_pk_fma_f32 v[128:129], v[128:129], v[132:133], v[196:197] op_sel_hi:[1,0,0]
	v_pk_mul_f32 v[126:127], v[118:119], v[126:127]
	v_pk_mul_f32 v[128:129], v[120:121], v[128:129]
	v_exp_f32_e32 v126, v126
	v_exp_f32_e32 v127, v127
	v_exp_f32_e32 v128, v128
	v_exp_f32_e32 v129, v129
	v_pk_add_f32 v[126:127], v[126:127], v[250:251] op_sel_hi:[1,0]
	v_pk_add_f32 v[128:129], v[128:129], v[250:251] op_sel_hi:[1,0]
	v_rcp_f32_e32 v126, v126
	v_rcp_f32_e32 v127, v127
	v_rcp_f32_e32 v128, v128
	v_rcp_f32_e32 v129, v129
	v_pk_mul_f32 v[126:127], v[118:119], v[126:127]
	v_pk_mul_f32 v[128:129], v[120:121], v[128:129]
	v_pk_mul_f32 v[126:127], v[122:123], v[126:127]
	v_pk_mul_f32 v[128:129], v[124:125], v[128:129]
	v_cvt_pk_bf16_f32 v126, v126, v127
	v_cvt_pk_bf16_f32 v127, v128, v129
	v_add_u32_e32 v131, 0x18c000, v199
	global_store_dwordx2 v131, v[126:127], s[68:69] offset:8
	v_pk_mul_f32 v[14:15], v[14:15], v[200:201] op_sel_hi:[1,0]
	v_pk_mul_f32 v[16:17], v[16:17], v[200:201] op_sel_hi:[1,0]
	v_pk_mul_f32 v[10:11], v[10:11], v[200:201] op_sel_hi:[1,0]
	v_pk_mul_f32 v[12:13], v[12:13], v[200:201] op_sel_hi:[1,0]
	v_pk_fma_f32 v[106:107], v[14:15], v[154:155], v[150:151]
	v_pk_fma_f32 v[108:109], v[16:17], v[156:157], v[152:153]
	v_pk_fma_f32 v[110:111], v[10:11], v[134:135], v[146:147]
	v_pk_fma_f32 v[112:113], v[12:13], v[136:137], v[148:149]
	v_fmac_f32_dpp v106, v14, v142 row_shr:1 row_mask:0xf bank_mask:0xf
	v_fmac_f32_dpp v107, v15, v143 row_shr:1 row_mask:0xf bank_mask:0xf
; __device__ __forceinline__ unsigned cvt_pk_bf16(float lo, float hi) { unsigned r; asm volatile("v_cvt_pk_bf16_f32 %0, %1, %2" : "=v"(r) : "v"(lo), "v"(hi)); return r; }
; __device__ __forceinline__ f32x4 gelu4(f32x4 v) { return (f32x4){gelu_t(v[0]), gelu_t(v[1]), gelu_t(v[2]), gelu_t(v[3])}; }
; template <int CTRL> __device__ __forceinline__ f32x4 dpp4(f32x4 v) { return (f32x4){dpp_f<CTRL>(v[0]), dpp_f<CTRL>(v[1]), dpp_f<CTRL>(v[2]), dpp_f<CTRL>(v[3])}; }
;     __device__ __forceinline__ void operator()(const f32x4 (&acc)[2][2][4][2], const Unit& u, int wr, int wc, int fr, int fq) const {
;     ...
;             for (int n = 0; n < 2; ++n) {
;                 const int c = cgl + 4 * n;
;                 const f32x4 wg0 = *(const f32x4*)(bias + c), wg1 = *(const f32x4*)(bias + NUPc + c), wg2 = *(const f32x4*)(bias + 2 * NUPc + c), bg = *(const f32x4*)(xin + c);
;                 const f32x4 wv0 = *(const f32x4*)(bias + DFFc + c), wv1 = *(const f32x4*)(bias + NUPc + DFFc + c), wv2 = *(const f32x4*)(bias + 2 * NUPc + DFFc + c), bv = *(const f32x4*)(xin + DFFc + c);
; #pragma unroll
;                 for (int ai = 0; ai < 2; ++ai) {
;                     f32x4 pg1 = (f32x4){0.f, 0.f, 0.f, 0.f}, pg2 = pg1, pv1 = pg1, pv2 = pg1;
; #pragma unroll
;                     for (int m = 0; m < 4; ++m) {
;                         const f32x4 g = acc[ai][0][m][n] * rs[ai][m], v = acc[ai][1][m][n] * rs[ai][m];
;                         const f32x4 g1 = dpp4<0x121>(g), g2 = dpp4<0x122>(g), v1 = dpp4<0x121>(v), v2 = dpp4<0x122>(v);
;                         const f32x4 gp1 = (fr >= 1) ? g1 : pg1, gp2 = (fr >= 2) ? g2 : pg2, vp1 = (fr >= 1) ? v1 : pv1, vp2 = (fr >= 2) ? v2 : pv2;
;                         const f32x4 cgt = bg + wg0 * g + wg1 * gp1 + wg2 * gp2, cvl = bv + wv0 * v + wv1 * vp1 + wv2 * vp2;
;                         const f32x4 o = gelu4(cgt) * cvl;
;                         typedef unsigned u32x2e __attribute__((ext_vector_type(2)));
;                         u32x2e w; w.x = cvt_pk_bf16(o[0], o[1]); w.y = cvt_pk_bf16(o[2], o[3]);
;                         if (!(m == 0 && fr < 2)) *(u32x2e*)((bf16_t*)O + (size_t)(row0 + ai * HALF + m * 16) * DFFc + c) = w;
;                         pg1 = g1; pg2 = g2; pv1 = v1; pv2 = v2;
;                     }
	v_fmac_f32_dpp v108, v16, v144 row_shr:1 row_mask:0xf bank_mask:0xf
	v_fmac_f32_dpp v109, v17, v145 row_shr:1 row_mask:0xf bank_mask:0xf
	v_fmac_f32_dpp v110, v10, v138 row_shr:1 row_mask:0xf bank_mask:0xf
	v_fmac_f32_dpp v111, v11, v139 row_shr:1 row_mask:0xf bank_mask:0xf
	v_fmac_f32_dpp v112, v12, v140 row_shr:1 row_mask:0xf bank_mask:0xf
	v_fmac_f32_dpp v113, v13, v141 row_shr:1 row_mask:0xf bank_mask:0xf
	v_fmac_f32_dpp v106, v14, v102 row_shr:2 row_mask:0xf bank_mask:0xf
	v_fmac_f32_dpp v107, v15, v103 row_shr:2 row_mask:0xf bank_mask:0xf
	v_fmac_f32_dpp v108, v16, v104 row_shr:2 row_mask:0xf bank_mask:0xf
	v_fmac_f32_dpp v109, v17, v105 row_shr:2 row_mask:0xf bank_mask:0xf
	v_fmac_f32_dpp v110, v10, v98 row_shr:2 row_mask:0xf bank_mask:0xf
	v_fmac_f32_dpp v111, v11, v99 row_shr:2 row_mask:0xf bank_mask:0xf
	v_fmac_f32_dpp v112, v12, v100 row_shr:2 row_mask:0xf bank_mask:0xf
	v_fmac_f32_dpp v113, v13, v101 row_shr:2 row_mask:0xf bank_mask:0xf
	v_fmac_f32_dpp v106, v22, v142 row_shl:15 row_mask:0xf bank_mask:0xf
	v_fmac_f32_dpp v107, v23, v143 row_shl:15 row_mask:0xf bank_mask:0xf
	v_fmac_f32_dpp v108, v24, v144 row_shl:15 row_mask:0xf bank_mask:0xf
	v_fmac_f32_dpp v109, v25, v145 row_shl:15 row_mask:0xf bank_mask:0xf
	v_fmac_f32_dpp v110, v18, v138 row_shl:15 row_mask:0xf bank_mask:0xf
	v_fmac_f32_dpp v111, v19, v139 row_shl:15 row_mask:0xf bank_mask:0xf
	v_fmac_f32_dpp v112, v20, v140 row_shl:15 row_mask:0xf bank_mask:0xf
	v_fmac_f32_dpp v113, v21, v141 row_shl:15 row_mask:0xf bank_mask:0xf
	v_fmac_f32_dpp v106, v22, v102 row_shl:14 row_mask:0xf bank_mask:0xf
	v_fmac_f32_dpp v107, v23, v103 row_shl:14 row_mask:0xf bank_mask:0xf
	v_fmac_f32_dpp v108, v24, v104 row_shl:14 row_mask:0xf bank_mask:0xf
	v_fmac_f32_dpp v109, v25, v105 row_shl:14 row_mask:0xf bank_mask:0xf
	v_fmac_f32_dpp v110, v18, v98 row_shl:14 row_mask:0xf bank_mask:0xf
	v_fmac_f32_dpp v111, v19, v99 row_shl:14 row_mask:0xf bank_mask:0xf
	v_fmac_f32_dpp v112, v20, v100 row_shl:14 row_mask:0xf bank_mask:0xf
	v_fmac_f32_dpp v113, v21, v101 row_shl:14 row_mask:0xf bank_mask:0xf
	v_pk_mul_f32 v[114:115], v[106:107], v[106:107]
	v_pk_mul_f32 v[116:117], v[108:109], v[108:109]
	v_pk_fma_f32 v[114:115], v[114:115], v[132:133], v[196:197] op_sel_hi:[1,0,0]
	v_pk_fma_f32 v[116:117], v[116:117], v[132:133], v[196:197] op_sel_hi:[1,0,0]
	v_pk_mul_f32 v[114:115], v[106:107], v[114:115]
	v_pk_mul_f32 v[116:117], v[108:109], v[116:117]
	v_exp_f32_e32 v114, v114
	v_exp_f32_e32 v115, v115
	v_exp_f32_e32 v116, v116
	v_exp_f32_e32 v117, v117
	v_pk_add_f32 v[114:115], v[114:115], v[250:251] op_sel_hi:[1,0]
	v_pk_add_f32 v[116:117], v[116:117], v[250:251] op_sel_hi:[1,0]
	v_rcp_f32_e32 v114, v114
	v_rcp_f32_e32 v115, v115
	v_rcp_f32_e32 v116, v116
	v_rcp_f32_e32 v117, v117
	v_pk_mul_f32 v[114:115], v[106:107], v[114:115]
	v_pk_mul_f32 v[116:117], v[108:109], v[116:117]
	v_pk_mul_f32 v[114:115], v[110:111], v[114:115]
	v_pk_mul_f32 v[116:117], v[112:113], v[116:117]
	v_cvt_pk_bf16_f32 v114, v114, v115
	v_cvt_pk_bf16_f32 v115, v116, v117
	v_add_u32_e32 v130, 0x1b8000, v199
	global_store_dwordx2 v130, v[114:115], s[68:69] offset:8
	v_pk_mul_f32 v[6:7], v[6:7], v[178:179] op_sel_hi:[1,0]
	v_pk_mul_f32 v[8:9], v[8:9], v[178:179] op_sel_hi:[1,0]
	v_pk_mul_f32 v[2:3], v[2:3], v[178:179] op_sel_hi:[1,0]
	v_pk_mul_f32 v[4:5], v[4:5], v[178:179] op_sel_hi:[1,0]
	v_pk_fma_f32 v[118:119], v[6:7], v[154:155], v[150:151]
	v_pk_fma_f32 v[120:121], v[8:9], v[156:157], v[152:153]
	v_pk_fma_f32 v[122:123], v[2:3], v[134:135], v[146:147]
	v_pk_fma_f32 v[124:125], v[4:5], v[136:137], v[148:149]
	v_fmac_f32_dpp v118, v6, v142 row_shr:1 row_mask:0xf bank_mask:0xf
	v_fmac_f32_dpp v119, v7, v143 row_shr:1 row_mask:0xf bank_mask:0xf
	v_fmac_f32_dpp v120, v8, v144 row_shr:1 row_mask:0xf bank_mask:0xf
	v_fmac_f32_dpp v121, v9, v145 row_shr:1 row_mask:0xf bank_mask:0xf
	v_fmac_f32_dpp v122, v2, v138 row_shr:1 row_mask:0xf bank_mask:0xf
	v_fmac_f32_dpp v123, v3, v139 row_shr:1 row_mask:0xf bank_mask:0xf
	v_fmac_f32_dpp v124, v4, v140 row_shr:1 row_mask:0xf bank_mask:0xf
	v_fmac_f32_dpp v125, v5, v141 row_shr:1 row_mask:0xf bank_mask:0xf
	v_fmac_f32_dpp v118, v6, v102 row_shr:2 row_mask:0xf bank_mask:0xf
	v_fmac_f32_dpp v119, v7, v103 row_shr:2 row_mask:0xf bank_mask:0xf
	v_fmac_f32_dpp v120, v8, v104 row_shr:2 row_mask:0xf bank_mask:0xf
	v_fmac_f32_dpp v121, v9, v105 row_shr:2 row_mask:0xf bank_mask:0xf
	v_fmac_f32_dpp v122, v2, v98 row_shr:2 row_mask:0xf bank_mask:0xf
	v_fmac_f32_dpp v123, v3, v99 row_shr:2 row_mask:0xf bank_mask:0xf
	v_fmac_f32_dpp v124, v4, v100 row_shr:2 row_mask:0xf bank_mask:0xf
	v_fmac_f32_dpp v125, v5, v101 row_shr:2 row_mask:0xf bank_mask:0xf
	v_fmac_f32_dpp v118, v14, v142 row_shl:15 row_mask:0xf bank_mask:0xf
	v_fmac_f32_dpp v119, v15, v143 row_shl:15 row_mask:0xf bank_mask:0xf
	v_fmac_f32_dpp v120, v16, v144 row_shl:15 row_mask:0xf bank_mask:0xf
	v_fmac_f32_dpp v121, v17, v145 row_shl:15 row_mask:0xf bank_mask:0xf
	v_fmac_f32_dpp v122, v10, v138 row_shl:15 row_mask:0xf bank_mask:0xf
	v_fmac_f32_dpp v123, v11, v139 row_shl:15 row_mask:0xf bank_mask:0xf
	v_fmac_f32_dpp v124, v12, v140 row_shl:15 row_mask:0xf bank_mask:0xf
	v_fmac_f32_dpp v125, v13, v141 row_shl:15 row_mask:0xf bank_mask:0xf
	v_fmac_f32_dpp v118, v14, v102 row_shl:14 row_mask:0xf bank_mask:0xf
	v_fmac_f32_dpp v119, v15, v103 row_shl:14 row_mask:0xf bank_mask:0xf
	v_fmac_f32_dpp v120, v16, v104 row_shl:14 row_mask:0xf bank_mask:0xf
	v_fmac_f32_dpp v121, v17, v105 row_shl:14 row_mask:0xf bank_mask:0xf
	v_fmac_f32_dpp v122, v10, v98 row_shl:14 row_mask:0xf bank_mask:0xf
	v_fmac_f32_dpp v123, v11, v99 row_shl:14 row_mask:0xf bank_mask:0xf
	v_fmac_f32_dpp v124, v12, v100 row_shl:14 row_mask:0xf bank_mask:0xf
	v_fmac_f32_dpp v125, v13, v101 row_shl:14 row_mask:0xf bank_mask:0xf
	v_pk_mul_f32 v[126:127], v[118:119], v[118:119]
	v_pk_mul_f32 v[128:129], v[120:121], v[120:121]
	v_pk_fma_f32 v[126:127], v[126:127], v[132:133], v[196:197] op_sel_hi:[1,0,0]
	v_pk_fma_f32 v[128:129], v[128:129], v[132:133], v[196:197] op_sel_hi:[1,0,0]
	v_pk_mul_f32 v[126:127], v[118:119], v[126:127]
	v_pk_mul_f32 v[128:129], v[120:121], v[128:129]
	v_exp_f32_e32 v126, v126
	v_exp_f32_e32 v127, v127
	v_exp_f32_e32 v128, v128
	v_exp_f32_e32 v129, v129
	v_pk_add_f32 v[126:127], v[126:127], v[250:251] op_sel_hi:[1,0]
	v_pk_add_f32 v[128:129], v[128:129], v[250:251] op_sel_hi:[1,0]
	v_rcp_f32_e32 v126, v126
	v_rcp_f32_e32 v127, v127
	v_rcp_f32_e32 v128, v128
	v_rcp_f32_e32 v129, v129
	v_pk_mul_f32 v[126:127], v[118:119], v[126:127]
	v_pk_mul_f32 v[128:129], v[120:121], v[128:129]
	v_pk_mul_f32 v[126:127], v[122:123], v[126:127]
	v_pk_mul_f32 v[128:129], v[124:125], v[128:129]
	v_cvt_pk_bf16_f32 v126, v126, v127
	v_cvt_pk_bf16_f32 v127, v128, v129
	v_add_u32_e32 v131, 0x1e4000, v199
	global_store_dwordx2 v131, v[126:127], s[68:69] offset:8
	s_andn2_b64 vcc, exec, s[8:9]
	s_mov_b64 s[8:9], -1
	s_cbranch_vccnz .LBB0_39
	s_andn2_b64 vcc, exec, s[2:3]
	s_cbranch_vccnz .LBB0_38
	s_barrier
	s_branch .LBB0_38
